# SwiGLU epilogue: next row group's 16 sum-of-squares partials loaded during the current group's compute (v[236:251]); packed 3-level sum
# speedup vs baseline: 1.0016x; 1.0016x over previous
.LBB0_413:
	v_lshl_add_u32 v144, s26, 8, v146
	v_ashrrev_i32_e32 v145, 31, v144
	v_lshlrev_b64 v[154:155], 6, v[144:145]
	v_lshl_add_u64 v[166:167], s[6:7], 0, v[154:155]
	global_load_dwordx4 v[154:157], v[166:167], off
	global_load_dwordx4 v[158:161], v[166:167], off offset:16
	global_load_dwordx4 v[162:165], v[166:167], off offset:32
	s_nop 0
	global_load_dwordx4 v[166:169], v[166:167], off offset:48
	v_mov_b32_e32 v174, v122
	v_mov_b32_e32 v175, v114
	v_mov_b32_e32 v114, v123
	v_mov_b32_e32 v172, v124
	v_mov_b32_e32 v173, v116
	v_mov_b32_e32 v116, v125
	v_mov_b32_e32 v124, v126
	v_mov_b32_e32 v125, v118
	v_mov_b32_e32 v118, v127
	v_mov_b32_e32 v127, v112
	v_mov_b32_e32 v112, v121
	v_mov_b32_e32 v126, v120
	v_lshl_or_b32 v170, s60, 7, v148
	v_mov_b64_e32 v[120:121], s[8:9]
	v_ashrrev_i32_e32 v171, 31, v170
	s_waitcnt vmcnt(0)
	v_mov_b32_e32 v122, v155
	v_mov_b32_e32 v123, v156
	v_mov_b32_e32 v155, v157
	v_mov_b32_e32 v156, v159
	v_mov_b32_e32 v157, v160
	v_mov_b32_e32 v159, v161
	v_pk_add_f32 v[122:123], v[122:123], v[154:155]
	v_pk_add_f32 v[154:155], v[156:157], v[158:159]
	v_pk_add_f32 v[122:123], v[122:123], v[122:123] op_sel:[0,1] op_sel_hi:[1,0]
	v_pk_add_f32 v[154:155], v[154:155], v[154:155] op_sel:[0,1] op_sel_hi:[1,0]
	v_add_f32_e32 v160, v162, v163
	v_add_f32_e32 v162, v164, v165
	v_mov_b32_e32 v161, v168
	v_mov_b32_e32 v163, v169
	v_mov_b32_e32 v123, v166
	v_mov_b32_e32 v155, v167
	v_pk_add_f32 v[156:157], v[160:161], v[162:163]
	v_pk_add_f32 v[122:123], v[122:123], v[154:155]
	v_mad_i64_i32 v[154:155], s[28:29], v144, s59, v[120:121]
	v_pk_add_f32 v[122:123], v[122:123], v[156:157]
	s_nop 0
	v_add_f32_e32 v122, v122, v123
	v_or_b32_e32 v252, 16, v144
	v_ashrrev_i32_e32 v253, 31, v252
	v_lshlrev_b64 v[252:253], 6, v[252:253]
	v_lshl_add_u64 v[254:255], s[6:7], 0, v[252:253]
	global_load_dwordx4 v[236:239], v[254:255], off
	global_load_dwordx4 v[240:243], v[254:255], off offset:16
	global_load_dwordx4 v[244:247], v[254:255], off offset:32
	global_load_dwordx4 v[248:251], v[254:255], off offset:48
	v_fmamk_f32 v122, v122, 0x3a800000, v152
	v_mul_f32_e32 v123, 0x4b800000, v122
	v_cmp_gt_f32_e32 vcc, s58, v122
	s_nop 1
	v_cndmask_b32_e32 v122, v122, v123, vcc
	v_rsq_f32_e32 v145, v122
	v_lshlrev_b64 v[122:123], 1, v[170:171]
	v_lshl_add_u64 v[154:155], v[154:155], 0, v[122:123]
	v_mul_f32_e32 v153, 0x45800000, v145
	v_cndmask_b32_e32 v156, v145, v153, vcc
	v_pk_mul_f32 v[158:159], v[172:173], v[156:157] op_sel_hi:[1,0]
	v_pk_mul_f32 v[116:117], v[116:117], v[156:157] op_sel_hi:[1,0]
	v_pk_mul_f32 v[124:125], v[124:125], v[156:157] op_sel_hi:[1,0]
	v_pk_mul_f32 v[118:119], v[118:119], v[156:157] op_sel_hi:[1,0]
	v_pk_mul_f32 v[112:113], v[112:113], v[156:157] op_sel_hi:[1,0]
	v_pk_mul_f32 v[114:115], v[114:115], v[156:157] op_sel_hi:[1,0]
	v_mul_f32_e32 v145, 0xbfb8aa3b, v159
	v_pk_mul_f32 v[126:127], v[126:127], v[156:157] op_sel_hi:[1,0]
	v_pk_mul_f32 v[160:161], v[174:175], v[156:157] op_sel_hi:[1,0]
	v_mul_f32_e32 v153, 0xbfb8aa3b, v117
	v_mul_f32_e32 v156, 0xbfb8aa3b, v125
	v_mul_f32_e32 v157, 0xbfb8aa3b, v119
	v_mul_f32_e32 v163, 0xbfb8aa3b, v113
	v_mul_f32_e32 v165, 0xbfb8aa3b, v115
	v_exp_f32_e32 v145, v145
	v_mul_f32_e32 v162, 0xbfb8aa3b, v127
	v_mul_f32_e32 v164, 0xbfb8aa3b, v161
	v_exp_f32_e32 v153, v153
	v_exp_f32_e32 v156, v156
	v_exp_f32_e32 v157, v157
	v_exp_f32_e32 v163, v163
	v_exp_f32_e32 v165, v165
	v_exp_f32_e32 v162, v162
	v_exp_f32_e32 v164, v164
	v_add_f32_e32 v145, 1.0, v145
	v_add_f32_e32 v153, 1.0, v153
	v_add_f32_e32 v156, 1.0, v156
	v_add_f32_e32 v157, 1.0, v157
	v_add_f32_e32 v163, 1.0, v163
	v_add_f32_e32 v165, 1.0, v165
	v_rcp_f32_e32 v145, v145
	v_add_f32_e32 v162, 1.0, v162
	v_add_f32_e32 v164, 1.0, v164
	v_rcp_f32_e32 v153, v153
	v_rcp_f32_e32 v156, v156
	v_rcp_f32_e32 v157, v157
	v_rcp_f32_e32 v163, v163
	v_rcp_f32_e32 v165, v165
	v_rcp_f32_e32 v162, v162
	v_rcp_f32_e32 v164, v164
	v_mul_f32_e32 v145, v159, v145
	v_mul_f32_e32 v117, v117, v153
	v_mul_f32_e32 v125, v125, v156
	v_mul_f32_e32 v119, v119, v157
	v_mul_f32_e32 v113, v113, v163
	v_mul_f32_e32 v115, v115, v165
	v_mul_f32_e32 v145, v158, v145
	v_or_b32_e32 v158, 16, v144
	v_mul_f32_e32 v127, v127, v162
	v_mul_f32_e32 v153, v161, v164
	v_mul_f32_e32 v116, v116, v117
	v_mul_f32_e32 v117, v124, v125
	v_mul_f32_e32 v118, v118, v119
	v_mul_f32_e32 v124, v112, v113
	v_mul_f32_e32 v115, v114, v115
	v_cvt_pk_bf16_f32 v112, v145, v116
	v_cvt_pk_bf16_f32 v113, v117, v118
	v_ashrrev_i32_e32 v159, 31, v158
	v_mul_f32_e32 v119, v126, v127
	v_mul_f32_e32 v125, v160, v153
	v_cvt_pk_bf16_f32 v114, v119, v124
	v_cvt_pk_bf16_f32 v115, v125, v115
	global_store_dwordx4 v[154:155], v[112:115], off
	v_mov_b32_e32 v160, v108
	v_mov_b32_e32 v161, v100
	v_mov_b32_e32 v100, v109
	v_mov_b32_e32 v108, v110
	v_mov_b32_e32 v109, v102
	v_mov_b32_e32 v102, v111
	v_mov_b32_e32 v110, v104
	v_mov_b32_e32 v111, v96
	v_mov_b32_e32 v96, v105
	v_mov_b32_e32 v104, v106
	v_mov_b32_e32 v105, v98
	v_mov_b32_e32 v98, v107
	s_waitcnt vmcnt(1)
	v_pk_add_f32 v[236:237], v[236:237], v[238:239]
	v_pk_add_f32 v[240:241], v[240:241], v[242:243]
	v_pk_add_f32 v[244:245], v[244:245], v[246:247]
	v_pk_add_f32 v[248:249], v[248:249], v[250:251]
	v_pk_add_f32 v[236:237], v[236:237], v[240:241]
	v_pk_add_f32 v[244:245], v[244:245], v[248:249]
	s_nop 0
	v_pk_add_f32 v[236:237], v[236:237], v[244:245]
	s_nop 0
	v_add_f32_e32 v106, v236, v237
	v_or_b32_e32 v252, 32, v144
	v_ashrrev_i32_e32 v253, 31, v252
	v_lshlrev_b64 v[252:253], 6, v[252:253]
	v_lshl_add_u64 v[254:255], s[6:7], 0, v[252:253]
	global_load_dwordx4 v[236:239], v[254:255], off
	global_load_dwordx4 v[240:243], v[254:255], off offset:16
	global_load_dwordx4 v[244:247], v[254:255], off offset:32
	global_load_dwordx4 v[248:251], v[254:255], off offset:48
	v_fmamk_f32 v106, v106, 0x3a800000, v152
	v_mul_f32_e32 v107, 0x4b800000, v106
	v_cmp_gt_f32_e32 vcc, s58, v106
	s_nop 1
	v_cndmask_b32_e32 v106, v106, v107, vcc
	v_rsq_f32_e32 v112, v106
	v_mad_i64_i32 v[106:107], s[28:29], v158, s59, v[120:121]
	v_lshl_add_u64 v[106:107], v[106:107], 0, v[122:123]
	v_mul_f32_e32 v113, 0x45800000, v112
	v_cndmask_b32_e32 v112, v112, v113, vcc
	v_pk_mul_f32 v[114:115], v[160:161], v[112:113] op_sel_hi:[1,0]
	v_pk_mul_f32 v[100:101], v[100:101], v[112:113] op_sel_hi:[1,0]
	v_pk_mul_f32 v[108:109], v[108:109], v[112:113] op_sel_hi:[1,0]
	v_pk_mul_f32 v[102:103], v[102:103], v[112:113] op_sel_hi:[1,0]
	v_pk_mul_f32 v[110:111], v[110:111], v[112:113] op_sel_hi:[1,0]
	v_pk_mul_f32 v[96:97], v[96:97], v[112:113] op_sel_hi:[1,0]
	v_pk_mul_f32 v[104:105], v[104:105], v[112:113] op_sel_hi:[1,0]
	v_pk_mul_f32 v[98:99], v[98:99], v[112:113] op_sel_hi:[1,0]
	v_mul_f32_e32 v112, 0xbfb8aa3b, v115
	v_mul_f32_e32 v113, 0xbfb8aa3b, v101
	v_mul_f32_e32 v116, 0xbfb8aa3b, v109
	v_mul_f32_e32 v119, 0xbfb8aa3b, v97
	v_exp_f32_e32 v112, v112
	v_mul_f32_e32 v117, 0xbfb8aa3b, v103
	v_mul_f32_e32 v125, 0xbfb8aa3b, v99
	v_exp_f32_e32 v113, v113
	v_exp_f32_e32 v116, v116
	v_exp_f32_e32 v119, v119
	v_mul_f32_e32 v118, 0xbfb8aa3b, v111
	v_mul_f32_e32 v124, 0xbfb8aa3b, v105
	v_exp_f32_e32 v117, v117
	v_exp_f32_e32 v125, v125
	v_exp_f32_e32 v118, v118
	v_exp_f32_e32 v124, v124
	v_add_f32_e32 v112, 1.0, v112
	v_add_f32_e32 v113, 1.0, v113
	v_add_f32_e32 v116, 1.0, v116
	v_add_f32_e32 v119, 1.0, v119
	v_rcp_f32_e32 v112, v112
	v_add_f32_e32 v117, 1.0, v117
	v_add_f32_e32 v125, 1.0, v125
	v_rcp_f32_e32 v113, v113
	v_rcp_f32_e32 v116, v116
	v_rcp_f32_e32 v119, v119
	v_add_f32_e32 v118, 1.0, v118
	v_add_f32_e32 v124, 1.0, v124
	v_rcp_f32_e32 v117, v117
	v_rcp_f32_e32 v125, v125
	v_rcp_f32_e32 v118, v118
	v_rcp_f32_e32 v124, v124
	v_mul_f32_e32 v112, v115, v112
	v_mul_f32_e32 v101, v101, v113
	v_mul_f32_e32 v109, v109, v116
	v_mul_f32_e32 v97, v97, v119
	v_mul_f32_e32 v112, v114, v112
	v_mul_f32_e32 v103, v103, v117
	v_mul_f32_e32 v99, v99, v125
	v_mul_f32_e32 v100, v100, v101
	v_mul_f32_e32 v101, v108, v109
	v_mul_f32_e32 v108, v96, v97
	v_cvt_pk_bf16_f32 v96, v112, v100
	v_or_b32_e32 v112, 32, v144
	v_mul_f32_e32 v111, v111, v118
	v_mul_f32_e32 v105, v105, v124
	v_mul_f32_e32 v102, v102, v103
	v_mul_f32_e32 v99, v98, v99
	v_cvt_pk_bf16_f32 v97, v101, v102
	v_ashrrev_i32_e32 v113, 31, v112
	v_mul_f32_e32 v103, v110, v111
	v_mul_f32_e32 v104, v104, v105
	v_cvt_pk_bf16_f32 v98, v103, v108
	v_cvt_pk_bf16_f32 v99, v104, v99
	global_store_dwordx4 v[106:107], v[96:99], off
	v_mov_b32_e32 v114, v92
	v_mov_b32_e32 v115, v84
	v_mov_b32_e32 v84, v93
	v_mov_b32_e32 v92, v94
	v_mov_b32_e32 v93, v86
	v_mov_b32_e32 v86, v95
	v_mov_b32_e32 v94, v88
	v_mov_b32_e32 v95, v80
	v_mov_b32_e32 v80, v89
	v_mov_b32_e32 v88, v90
	v_mov_b32_e32 v89, v82
	v_mov_b32_e32 v82, v91
	s_waitcnt vmcnt(1)
	v_pk_add_f32 v[236:237], v[236:237], v[238:239]
	v_pk_add_f32 v[240:241], v[240:241], v[242:243]
	v_pk_add_f32 v[244:245], v[244:245], v[246:247]
	v_pk_add_f32 v[248:249], v[248:249], v[250:251]
	v_pk_add_f32 v[236:237], v[236:237], v[240:241]
	v_pk_add_f32 v[244:245], v[244:245], v[248:249]
	s_nop 0
	v_pk_add_f32 v[236:237], v[236:237], v[244:245]
	s_nop 0
	v_add_f32_e32 v90, v236, v237
	v_or_b32_e32 v252, 48, v144
	v_ashrrev_i32_e32 v253, 31, v252
	v_lshlrev_b64 v[252:253], 6, v[252:253]
	v_lshl_add_u64 v[254:255], s[6:7], 0, v[252:253]
	global_load_dwordx4 v[236:239], v[254:255], off
	global_load_dwordx4 v[240:243], v[254:255], off offset:16
	global_load_dwordx4 v[244:247], v[254:255], off offset:32
	global_load_dwordx4 v[248:251], v[254:255], off offset:48
	v_fmamk_f32 v90, v90, 0x3a800000, v152
	v_mul_f32_e32 v91, 0x4b800000, v90
	v_cmp_gt_f32_e32 vcc, s58, v90
	s_nop 1
	v_cndmask_b32_e32 v90, v90, v91, vcc
	v_rsq_f32_e32 v96, v90
	v_mad_i64_i32 v[90:91], s[28:29], v112, s59, v[120:121]
	v_lshl_add_u64 v[90:91], v[90:91], 0, v[122:123]
	v_mul_f32_e32 v97, 0x45800000, v96
	v_cndmask_b32_e32 v96, v96, v97, vcc
	v_pk_mul_f32 v[98:99], v[114:115], v[96:97] op_sel_hi:[1,0]
	v_pk_mul_f32 v[84:85], v[84:85], v[96:97] op_sel_hi:[1,0]
	v_pk_mul_f32 v[92:93], v[92:93], v[96:97] op_sel_hi:[1,0]
	v_pk_mul_f32 v[86:87], v[86:87], v[96:97] op_sel_hi:[1,0]
	v_pk_mul_f32 v[94:95], v[94:95], v[96:97] op_sel_hi:[1,0]
	v_pk_mul_f32 v[80:81], v[80:81], v[96:97] op_sel_hi:[1,0]
	v_pk_mul_f32 v[88:89], v[88:89], v[96:97] op_sel_hi:[1,0]
	v_pk_mul_f32 v[82:83], v[82:83], v[96:97] op_sel_hi:[1,0]
	v_mul_f32_e32 v96, 0xbfb8aa3b, v99
	v_mul_f32_e32 v97, 0xbfb8aa3b, v85
	v_mul_f32_e32 v100, 0xbfb8aa3b, v93
	v_mul_f32_e32 v103, 0xbfb8aa3b, v81
	v_exp_f32_e32 v96, v96
	v_mul_f32_e32 v101, 0xbfb8aa3b, v87
	v_mul_f32_e32 v105, 0xbfb8aa3b, v83
	v_exp_f32_e32 v97, v97
	v_exp_f32_e32 v100, v100
	v_exp_f32_e32 v103, v103
	v_mul_f32_e32 v102, 0xbfb8aa3b, v95
	v_mul_f32_e32 v104, 0xbfb8aa3b, v89
	v_exp_f32_e32 v101, v101
	v_exp_f32_e32 v105, v105
	v_exp_f32_e32 v102, v102
	v_exp_f32_e32 v104, v104
	v_add_f32_e32 v96, 1.0, v96
	v_add_f32_e32 v97, 1.0, v97
	v_add_f32_e32 v100, 1.0, v100
	v_add_f32_e32 v103, 1.0, v103
	v_rcp_f32_e32 v96, v96
	v_add_f32_e32 v101, 1.0, v101
	v_add_f32_e32 v105, 1.0, v105
	v_rcp_f32_e32 v97, v97
	v_rcp_f32_e32 v100, v100
	v_rcp_f32_e32 v103, v103
	v_add_f32_e32 v102, 1.0, v102
	v_add_f32_e32 v104, 1.0, v104
	v_rcp_f32_e32 v101, v101
	v_rcp_f32_e32 v105, v105
	v_rcp_f32_e32 v102, v102
	v_rcp_f32_e32 v104, v104
	v_mul_f32_e32 v96, v99, v96
	v_mul_f32_e32 v85, v85, v97
	v_mul_f32_e32 v93, v93, v100
	v_mul_f32_e32 v81, v81, v103
	v_mul_f32_e32 v96, v98, v96
	v_mul_f32_e32 v87, v87, v101
	v_mul_f32_e32 v83, v83, v105
	v_mul_f32_e32 v84, v84, v85
	v_mul_f32_e32 v85, v92, v93
	v_mul_f32_e32 v92, v80, v81
	v_cvt_pk_bf16_f32 v80, v96, v84
	v_or_b32_e32 v96, 48, v144
	v_mul_f32_e32 v95, v95, v102
	v_mul_f32_e32 v89, v89, v104
	v_mul_f32_e32 v86, v86, v87
	v_mul_f32_e32 v83, v82, v83
	v_cvt_pk_bf16_f32 v81, v85, v86
	v_ashrrev_i32_e32 v97, 31, v96
	v_mul_f32_e32 v87, v94, v95
	v_mul_f32_e32 v88, v88, v89
	v_cvt_pk_bf16_f32 v82, v87, v92
	v_cvt_pk_bf16_f32 v83, v88, v83
	global_store_dwordx4 v[90:91], v[80:83], off
	v_mov_b32_e32 v98, v76
	v_mov_b32_e32 v99, v68
	v_mov_b32_e32 v68, v77
	v_mov_b32_e32 v76, v78
	v_mov_b32_e32 v77, v70
	v_mov_b32_e32 v70, v79
	v_mov_b32_e32 v78, v72
	v_mov_b32_e32 v79, v64
	v_mov_b32_e32 v64, v73
	v_mov_b32_e32 v72, v74
	v_mov_b32_e32 v73, v66
	v_mov_b32_e32 v66, v75
	s_waitcnt vmcnt(1)
	v_pk_add_f32 v[236:237], v[236:237], v[238:239]
	v_pk_add_f32 v[240:241], v[240:241], v[242:243]
	v_pk_add_f32 v[244:245], v[244:245], v[246:247]
	v_pk_add_f32 v[248:249], v[248:249], v[250:251]
	v_pk_add_f32 v[236:237], v[236:237], v[240:241]
	v_pk_add_f32 v[244:245], v[244:245], v[248:249]
	s_nop 0
	v_pk_add_f32 v[236:237], v[236:237], v[244:245]
	s_nop 0
	v_add_f32_e32 v74, v236, v237
	v_add_u32_e32 v252, 0x80, v144
	v_ashrrev_i32_e32 v253, 31, v252
	v_lshlrev_b64 v[252:253], 6, v[252:253]
	v_lshl_add_u64 v[254:255], s[6:7], 0, v[252:253]
	global_load_dwordx4 v[236:239], v[254:255], off
	global_load_dwordx4 v[240:243], v[254:255], off offset:16
	global_load_dwordx4 v[244:247], v[254:255], off offset:32
	global_load_dwordx4 v[248:251], v[254:255], off offset:48
	v_fmamk_f32 v74, v74, 0x3a800000, v152
	v_mul_f32_e32 v75, 0x4b800000, v74
	v_cmp_gt_f32_e32 vcc, s58, v74
	s_nop 1
	v_cndmask_b32_e32 v74, v74, v75, vcc
	v_rsq_f32_e32 v80, v74
	v_mad_i64_i32 v[74:75], s[28:29], v96, s59, v[120:121]
	v_lshl_add_u64 v[74:75], v[74:75], 0, v[122:123]
	v_mul_f32_e32 v81, 0x45800000, v80
	v_cndmask_b32_e32 v80, v80, v81, vcc
	v_pk_mul_f32 v[82:83], v[98:99], v[80:81] op_sel_hi:[1,0]
	v_pk_mul_f32 v[68:69], v[68:69], v[80:81] op_sel_hi:[1,0]
	v_pk_mul_f32 v[76:77], v[76:77], v[80:81] op_sel_hi:[1,0]
	v_pk_mul_f32 v[70:71], v[70:71], v[80:81] op_sel_hi:[1,0]
	v_pk_mul_f32 v[78:79], v[78:79], v[80:81] op_sel_hi:[1,0]
	v_pk_mul_f32 v[64:65], v[64:65], v[80:81] op_sel_hi:[1,0]
	v_pk_mul_f32 v[72:73], v[72:73], v[80:81] op_sel_hi:[1,0]
	v_pk_mul_f32 v[66:67], v[66:67], v[80:81] op_sel_hi:[1,0]
	v_mul_f32_e32 v80, 0xbfb8aa3b, v83
	v_mul_f32_e32 v81, 0xbfb8aa3b, v69
	v_mul_f32_e32 v84, 0xbfb8aa3b, v77
	v_mul_f32_e32 v87, 0xbfb8aa3b, v65
	v_exp_f32_e32 v80, v80
	v_mul_f32_e32 v85, 0xbfb8aa3b, v71
	v_mul_f32_e32 v89, 0xbfb8aa3b, v67
	v_exp_f32_e32 v81, v81
	v_exp_f32_e32 v84, v84
	v_exp_f32_e32 v87, v87
	v_mul_f32_e32 v86, 0xbfb8aa3b, v79
	v_mul_f32_e32 v88, 0xbfb8aa3b, v73
	v_exp_f32_e32 v85, v85
	v_exp_f32_e32 v89, v89
	v_exp_f32_e32 v86, v86
	v_exp_f32_e32 v88, v88
	v_add_f32_e32 v80, 1.0, v80
	v_add_f32_e32 v81, 1.0, v81
	v_add_f32_e32 v84, 1.0, v84
	v_add_f32_e32 v87, 1.0, v87
	v_rcp_f32_e32 v80, v80
	v_add_f32_e32 v85, 1.0, v85
	v_add_f32_e32 v89, 1.0, v89
	v_rcp_f32_e32 v81, v81
	v_rcp_f32_e32 v84, v84
	v_rcp_f32_e32 v87, v87
	v_add_f32_e32 v86, 1.0, v86
	v_add_f32_e32 v88, 1.0, v88
	v_rcp_f32_e32 v85, v85
	v_rcp_f32_e32 v89, v89
	v_rcp_f32_e32 v86, v86
	v_rcp_f32_e32 v88, v88
	v_mul_f32_e32 v80, v83, v80
	v_mul_f32_e32 v69, v69, v81
	v_mul_f32_e32 v77, v77, v84
	v_mul_f32_e32 v65, v65, v87
	v_mul_f32_e32 v80, v82, v80
	v_mul_f32_e32 v71, v71, v85
	v_mul_f32_e32 v67, v67, v89
	v_mul_f32_e32 v68, v68, v69
	v_mul_f32_e32 v69, v76, v77
	v_mul_f32_e32 v76, v64, v65
	v_cvt_pk_bf16_f32 v64, v80, v68
	v_add_u32_e32 v80, 0x80, v144
	v_mul_f32_e32 v79, v79, v86
	v_mul_f32_e32 v73, v73, v88
	v_mul_f32_e32 v70, v70, v71
	v_mul_f32_e32 v67, v66, v67
	v_cvt_pk_bf16_f32 v65, v69, v70
	v_ashrrev_i32_e32 v81, 31, v80
	v_mul_f32_e32 v71, v78, v79
	v_mul_f32_e32 v72, v72, v73
	v_cvt_pk_bf16_f32 v66, v71, v76
	v_cvt_pk_bf16_f32 v67, v72, v67
	global_store_dwordx4 v[74:75], v[64:67], off
	v_mov_b32_e32 v82, v60
	v_mov_b32_e32 v83, v52
	v_mov_b32_e32 v52, v61
	v_mov_b32_e32 v60, v62
	v_mov_b32_e32 v61, v54
	v_mov_b32_e32 v54, v63
	v_mov_b32_e32 v62, v56
	v_mov_b32_e32 v63, v48
	v_mov_b32_e32 v48, v57
	v_mov_b32_e32 v56, v58
	v_mov_b32_e32 v57, v50
	v_mov_b32_e32 v50, v59
	s_waitcnt vmcnt(1)
	v_pk_add_f32 v[236:237], v[236:237], v[238:239]
	v_pk_add_f32 v[240:241], v[240:241], v[242:243]
	v_pk_add_f32 v[244:245], v[244:245], v[246:247]
	v_pk_add_f32 v[248:249], v[248:249], v[250:251]
	v_pk_add_f32 v[236:237], v[236:237], v[240:241]
	v_pk_add_f32 v[244:245], v[244:245], v[248:249]
	s_nop 0
	v_pk_add_f32 v[236:237], v[236:237], v[244:245]
	s_nop 0
	v_add_f32_e32 v58, v236, v237
	v_add_u32_e32 v252, 0x90, v144
	v_ashrrev_i32_e32 v253, 31, v252
	v_lshlrev_b64 v[252:253], 6, v[252:253]
	v_lshl_add_u64 v[254:255], s[6:7], 0, v[252:253]
	global_load_dwordx4 v[236:239], v[254:255], off
	global_load_dwordx4 v[240:243], v[254:255], off offset:16
	global_load_dwordx4 v[244:247], v[254:255], off offset:32
	global_load_dwordx4 v[248:251], v[254:255], off offset:48
	v_fmamk_f32 v58, v58, 0x3a800000, v152
	v_mul_f32_e32 v59, 0x4b800000, v58
	v_cmp_gt_f32_e32 vcc, s58, v58
	s_nop 1
	v_cndmask_b32_e32 v58, v58, v59, vcc
	v_rsq_f32_e32 v64, v58
	v_mad_i64_i32 v[58:59], s[28:29], v80, s59, v[120:121]
	v_lshl_add_u64 v[58:59], v[58:59], 0, v[122:123]
	v_mul_f32_e32 v65, 0x45800000, v64
	v_cndmask_b32_e32 v64, v64, v65, vcc
	v_pk_mul_f32 v[66:67], v[82:83], v[64:65] op_sel_hi:[1,0]
	v_pk_mul_f32 v[52:53], v[52:53], v[64:65] op_sel_hi:[1,0]
	v_pk_mul_f32 v[60:61], v[60:61], v[64:65] op_sel_hi:[1,0]
	v_pk_mul_f32 v[54:55], v[54:55], v[64:65] op_sel_hi:[1,0]
	v_pk_mul_f32 v[62:63], v[62:63], v[64:65] op_sel_hi:[1,0]
	v_pk_mul_f32 v[48:49], v[48:49], v[64:65] op_sel_hi:[1,0]
	v_pk_mul_f32 v[56:57], v[56:57], v[64:65] op_sel_hi:[1,0]
	v_pk_mul_f32 v[50:51], v[50:51], v[64:65] op_sel_hi:[1,0]
	v_mul_f32_e32 v64, 0xbfb8aa3b, v67
	v_mul_f32_e32 v65, 0xbfb8aa3b, v53
	v_mul_f32_e32 v68, 0xbfb8aa3b, v61
	v_mul_f32_e32 v71, 0xbfb8aa3b, v49
	v_exp_f32_e32 v64, v64
	v_mul_f32_e32 v69, 0xbfb8aa3b, v55
	v_mul_f32_e32 v73, 0xbfb8aa3b, v51
	v_exp_f32_e32 v65, v65
	v_exp_f32_e32 v68, v68
	v_exp_f32_e32 v71, v71
	v_mul_f32_e32 v70, 0xbfb8aa3b, v63
	v_mul_f32_e32 v72, 0xbfb8aa3b, v57
	v_exp_f32_e32 v69, v69
	v_exp_f32_e32 v73, v73
	v_exp_f32_e32 v70, v70
	v_exp_f32_e32 v72, v72
	v_add_f32_e32 v64, 1.0, v64
	v_add_f32_e32 v65, 1.0, v65
	v_add_f32_e32 v68, 1.0, v68
	v_add_f32_e32 v71, 1.0, v71
	v_rcp_f32_e32 v64, v64
	v_add_f32_e32 v69, 1.0, v69
	v_add_f32_e32 v73, 1.0, v73
	v_rcp_f32_e32 v65, v65
	v_rcp_f32_e32 v68, v68
	v_rcp_f32_e32 v71, v71
	v_add_f32_e32 v70, 1.0, v70
	v_add_f32_e32 v72, 1.0, v72
	v_rcp_f32_e32 v69, v69
	v_rcp_f32_e32 v73, v73
	v_rcp_f32_e32 v70, v70
	v_rcp_f32_e32 v72, v72
	v_mul_f32_e32 v64, v67, v64
	v_mul_f32_e32 v53, v53, v65
	v_mul_f32_e32 v61, v61, v68
	v_mul_f32_e32 v49, v49, v71
	v_mul_f32_e32 v64, v66, v64
	v_mul_f32_e32 v55, v55, v69
	v_mul_f32_e32 v51, v51, v73
	v_mul_f32_e32 v52, v52, v53
	v_mul_f32_e32 v53, v60, v61
	v_mul_f32_e32 v60, v48, v49
	v_cvt_pk_bf16_f32 v48, v64, v52
	v_add_u32_e32 v64, 0x90, v144
	v_mul_f32_e32 v63, v63, v70
	v_mul_f32_e32 v57, v57, v72
	v_mul_f32_e32 v54, v54, v55
	v_mul_f32_e32 v51, v50, v51
	v_cvt_pk_bf16_f32 v49, v53, v54
	v_ashrrev_i32_e32 v65, 31, v64
	v_mul_f32_e32 v55, v62, v63
	v_mul_f32_e32 v56, v56, v57
	v_cvt_pk_bf16_f32 v50, v55, v60
	v_cvt_pk_bf16_f32 v51, v56, v51
	global_store_dwordx4 v[58:59], v[48:51], off
	v_mov_b32_e32 v66, v44
	v_mov_b32_e32 v67, v36
	v_mov_b32_e32 v36, v45
	v_mov_b32_e32 v44, v46
	v_mov_b32_e32 v45, v38
	v_mov_b32_e32 v38, v47
	v_mov_b32_e32 v46, v40
	v_mov_b32_e32 v47, v32
	v_mov_b32_e32 v32, v41
	v_mov_b32_e32 v40, v42
	v_mov_b32_e32 v41, v34
	v_mov_b32_e32 v34, v43
	s_waitcnt vmcnt(1)
	v_pk_add_f32 v[236:237], v[236:237], v[238:239]
	v_pk_add_f32 v[240:241], v[240:241], v[242:243]
	v_pk_add_f32 v[244:245], v[244:245], v[246:247]
	v_pk_add_f32 v[248:249], v[248:249], v[250:251]
	v_pk_add_f32 v[236:237], v[236:237], v[240:241]
	v_pk_add_f32 v[244:245], v[244:245], v[248:249]
	s_nop 0
	v_pk_add_f32 v[236:237], v[236:237], v[244:245]
	s_nop 0
	v_add_f32_e32 v42, v236, v237
	v_add_u32_e32 v252, 0xa0, v144
	v_ashrrev_i32_e32 v253, 31, v252
	v_lshlrev_b64 v[252:253], 6, v[252:253]
	v_lshl_add_u64 v[254:255], s[6:7], 0, v[252:253]
	global_load_dwordx4 v[236:239], v[254:255], off
	global_load_dwordx4 v[240:243], v[254:255], off offset:16
	global_load_dwordx4 v[244:247], v[254:255], off offset:32
	global_load_dwordx4 v[248:251], v[254:255], off offset:48
	v_fmamk_f32 v42, v42, 0x3a800000, v152
	v_mul_f32_e32 v43, 0x4b800000, v42
	v_cmp_gt_f32_e32 vcc, s58, v42
	s_nop 1
	v_cndmask_b32_e32 v42, v42, v43, vcc
	v_rsq_f32_e32 v48, v42
	v_mad_i64_i32 v[42:43], s[28:29], v64, s59, v[120:121]
	v_lshl_add_u64 v[42:43], v[42:43], 0, v[122:123]
	v_mul_f32_e32 v49, 0x45800000, v48
	v_cndmask_b32_e32 v48, v48, v49, vcc
	v_pk_mul_f32 v[50:51], v[66:67], v[48:49] op_sel_hi:[1,0]
	v_pk_mul_f32 v[36:37], v[36:37], v[48:49] op_sel_hi:[1,0]
	v_pk_mul_f32 v[44:45], v[44:45], v[48:49] op_sel_hi:[1,0]
	v_pk_mul_f32 v[38:39], v[38:39], v[48:49] op_sel_hi:[1,0]
	v_pk_mul_f32 v[46:47], v[46:47], v[48:49] op_sel_hi:[1,0]
	v_pk_mul_f32 v[32:33], v[32:33], v[48:49] op_sel_hi:[1,0]
	v_pk_mul_f32 v[40:41], v[40:41], v[48:49] op_sel_hi:[1,0]
	v_pk_mul_f32 v[34:35], v[34:35], v[48:49] op_sel_hi:[1,0]
	v_mul_f32_e32 v48, 0xbfb8aa3b, v51
	v_mul_f32_e32 v49, 0xbfb8aa3b, v37
	v_mul_f32_e32 v52, 0xbfb8aa3b, v45
	v_mul_f32_e32 v55, 0xbfb8aa3b, v33
	v_exp_f32_e32 v48, v48
	v_mul_f32_e32 v53, 0xbfb8aa3b, v39
	v_mul_f32_e32 v57, 0xbfb8aa3b, v35
	v_exp_f32_e32 v49, v49
	v_exp_f32_e32 v52, v52
	v_exp_f32_e32 v55, v55
	v_mul_f32_e32 v54, 0xbfb8aa3b, v47
	v_mul_f32_e32 v56, 0xbfb8aa3b, v41
	v_exp_f32_e32 v53, v53
	v_exp_f32_e32 v57, v57
	v_exp_f32_e32 v54, v54
	v_exp_f32_e32 v56, v56
	v_add_f32_e32 v48, 1.0, v48
	v_add_f32_e32 v49, 1.0, v49
	v_add_f32_e32 v52, 1.0, v52
	v_add_f32_e32 v55, 1.0, v55
	v_rcp_f32_e32 v48, v48
	v_add_f32_e32 v53, 1.0, v53
	v_add_f32_e32 v57, 1.0, v57
	v_rcp_f32_e32 v49, v49
	v_rcp_f32_e32 v52, v52
	v_rcp_f32_e32 v55, v55
	v_add_f32_e32 v54, 1.0, v54
	v_add_f32_e32 v56, 1.0, v56
	v_rcp_f32_e32 v53, v53
	v_rcp_f32_e32 v57, v57
	v_rcp_f32_e32 v54, v54
	v_rcp_f32_e32 v56, v56
	v_mul_f32_e32 v48, v51, v48
	v_mul_f32_e32 v37, v37, v49
	v_mul_f32_e32 v45, v45, v52
	v_mul_f32_e32 v33, v33, v55
	v_mul_f32_e32 v48, v50, v48
	v_mul_f32_e32 v39, v39, v53
	v_mul_f32_e32 v35, v35, v57
	v_mul_f32_e32 v36, v36, v37
	v_mul_f32_e32 v37, v44, v45
	v_mul_f32_e32 v44, v32, v33
	v_cvt_pk_bf16_f32 v32, v48, v36
	v_add_u32_e32 v48, 0xa0, v144
	v_mul_f32_e32 v47, v47, v54
	v_mul_f32_e32 v41, v41, v56
	v_mul_f32_e32 v38, v38, v39
	v_mul_f32_e32 v35, v34, v35
	v_cvt_pk_bf16_f32 v33, v37, v38
	v_ashrrev_i32_e32 v49, 31, v48
	v_mul_f32_e32 v39, v46, v47
	v_mul_f32_e32 v40, v40, v41
	v_cvt_pk_bf16_f32 v34, v39, v44
	v_cvt_pk_bf16_f32 v35, v40, v35
	global_store_dwordx4 v[42:43], v[32:35], off
	v_mov_b32_e32 v50, v28
	v_mov_b32_e32 v51, v20
	v_mov_b32_e32 v20, v29
	v_mov_b32_e32 v28, v30
	v_mov_b32_e32 v29, v22
	v_mov_b32_e32 v22, v31
	v_mov_b32_e32 v30, v24
	v_mov_b32_e32 v31, v16
	v_mov_b32_e32 v16, v25
	v_mov_b32_e32 v24, v26
	v_mov_b32_e32 v25, v18
	v_mov_b32_e32 v18, v27
	s_waitcnt vmcnt(1)
	v_pk_add_f32 v[236:237], v[236:237], v[238:239]
	v_pk_add_f32 v[240:241], v[240:241], v[242:243]
	v_pk_add_f32 v[244:245], v[244:245], v[246:247]
	v_pk_add_f32 v[248:249], v[248:249], v[250:251]
	v_pk_add_f32 v[236:237], v[236:237], v[240:241]
	v_pk_add_f32 v[244:245], v[244:245], v[248:249]
	s_nop 0
	v_pk_add_f32 v[236:237], v[236:237], v[244:245]
	s_nop 0
	v_add_f32_e32 v26, v236, v237
	v_add_u32_e32 v252, 0xb0, v144
	v_ashrrev_i32_e32 v253, 31, v252
	v_lshlrev_b64 v[252:253], 6, v[252:253]
	v_lshl_add_u64 v[254:255], s[6:7], 0, v[252:253]
	global_load_dwordx4 v[236:239], v[254:255], off
	global_load_dwordx4 v[240:243], v[254:255], off offset:16
	global_load_dwordx4 v[244:247], v[254:255], off offset:32
	global_load_dwordx4 v[248:251], v[254:255], off offset:48
	v_fmamk_f32 v26, v26, 0x3a800000, v152
	v_mul_f32_e32 v27, 0x4b800000, v26
	v_cmp_gt_f32_e32 vcc, s58, v26
	s_nop 1
	v_cndmask_b32_e32 v26, v26, v27, vcc
	v_rsq_f32_e32 v32, v26
	v_mad_i64_i32 v[26:27], s[28:29], v48, s59, v[120:121]
	v_lshl_add_u64 v[26:27], v[26:27], 0, v[122:123]
	v_mul_f32_e32 v33, 0x45800000, v32
	v_cndmask_b32_e32 v32, v32, v33, vcc
	v_pk_mul_f32 v[34:35], v[50:51], v[32:33] op_sel_hi:[1,0]
	v_pk_mul_f32 v[20:21], v[20:21], v[32:33] op_sel_hi:[1,0]
	v_pk_mul_f32 v[28:29], v[28:29], v[32:33] op_sel_hi:[1,0]
	v_pk_mul_f32 v[22:23], v[22:23], v[32:33] op_sel_hi:[1,0]
	v_pk_mul_f32 v[30:31], v[30:31], v[32:33] op_sel_hi:[1,0]
	v_pk_mul_f32 v[16:17], v[16:17], v[32:33] op_sel_hi:[1,0]
	v_pk_mul_f32 v[24:25], v[24:25], v[32:33] op_sel_hi:[1,0]
	v_pk_mul_f32 v[18:19], v[18:19], v[32:33] op_sel_hi:[1,0]
	v_mul_f32_e32 v32, 0xbfb8aa3b, v35
	v_mul_f32_e32 v33, 0xbfb8aa3b, v21
	v_mul_f32_e32 v36, 0xbfb8aa3b, v29
	v_mul_f32_e32 v39, 0xbfb8aa3b, v17
	v_exp_f32_e32 v32, v32
	v_mul_f32_e32 v37, 0xbfb8aa3b, v23
	v_mul_f32_e32 v41, 0xbfb8aa3b, v19
	v_exp_f32_e32 v33, v33
	v_exp_f32_e32 v36, v36
	v_exp_f32_e32 v39, v39
	v_mul_f32_e32 v38, 0xbfb8aa3b, v31
	v_mul_f32_e32 v40, 0xbfb8aa3b, v25
	v_exp_f32_e32 v37, v37
	v_exp_f32_e32 v41, v41
	v_exp_f32_e32 v38, v38
	v_exp_f32_e32 v40, v40
	v_add_f32_e32 v32, 1.0, v32
	v_add_f32_e32 v33, 1.0, v33
	v_add_f32_e32 v36, 1.0, v36
	v_add_f32_e32 v39, 1.0, v39
	v_rcp_f32_e32 v32, v32
	v_add_f32_e32 v37, 1.0, v37
	v_add_f32_e32 v41, 1.0, v41
	v_rcp_f32_e32 v33, v33
	v_rcp_f32_e32 v36, v36
	v_rcp_f32_e32 v39, v39
	v_add_f32_e32 v38, 1.0, v38
	v_add_f32_e32 v40, 1.0, v40
	v_rcp_f32_e32 v37, v37
	v_rcp_f32_e32 v41, v41
	v_rcp_f32_e32 v38, v38
	v_rcp_f32_e32 v40, v40
	v_mul_f32_e32 v32, v35, v32
	v_mul_f32_e32 v21, v21, v33
	v_mul_f32_e32 v29, v29, v36
	v_mul_f32_e32 v17, v17, v39
	v_mul_f32_e32 v32, v34, v32
	v_mul_f32_e32 v23, v23, v37
	v_mul_f32_e32 v19, v19, v41
	v_mul_f32_e32 v20, v20, v21
	v_mul_f32_e32 v21, v28, v29
	v_mul_f32_e32 v28, v16, v17
	v_cvt_pk_bf16_f32 v16, v32, v20
	v_add_u32_e32 v32, 0xb0, v144
	v_mul_f32_e32 v31, v31, v38
	v_mul_f32_e32 v25, v25, v40
	v_mul_f32_e32 v22, v22, v23
	v_mul_f32_e32 v19, v18, v19
	v_cvt_pk_bf16_f32 v17, v21, v22
	v_ashrrev_i32_e32 v33, 31, v32
	v_mul_f32_e32 v23, v30, v31
	v_mul_f32_e32 v24, v24, v25
	v_cvt_pk_bf16_f32 v18, v23, v28
	v_cvt_pk_bf16_f32 v19, v24, v19
	global_store_dwordx4 v[26:27], v[16:19], off
	v_mov_b32_e32 v34, v12
	v_mov_b32_e32 v35, v4
	v_mov_b32_e32 v4, v13
	v_mov_b32_e32 v12, v14
	v_mov_b32_e32 v13, v6
	v_mov_b32_e32 v6, v15
	v_mov_b32_e32 v14, v8
	v_mov_b32_e32 v15, v0
	v_mov_b32_e32 v0, v9
	v_mov_b32_e32 v8, v10
	v_mov_b32_e32 v9, v2
	v_mov_b32_e32 v2, v11
	s_waitcnt vmcnt(1)
	v_pk_add_f32 v[236:237], v[236:237], v[238:239]
	v_pk_add_f32 v[240:241], v[240:241], v[242:243]
	v_pk_add_f32 v[244:245], v[244:245], v[246:247]
	v_pk_add_f32 v[248:249], v[248:249], v[250:251]
	v_pk_add_f32 v[236:237], v[236:237], v[240:241]
	v_pk_add_f32 v[244:245], v[244:245], v[248:249]
	s_nop 0
	v_pk_add_f32 v[236:237], v[236:237], v[244:245]
	s_nop 0
	v_add_f32_e32 v10, v236, v237
	v_fmamk_f32 v10, v10, 0x3a800000, v152
	v_mul_f32_e32 v11, 0x4b800000, v10
	v_cmp_gt_f32_e32 vcc, s58, v10
	s_nop 1
	v_cndmask_b32_e32 v10, v10, v11, vcc
	v_rsq_f32_e32 v16, v10
	v_mad_i64_i32 v[10:11], s[28:29], v32, s59, v[120:121]
	v_lshl_add_u64 v[10:11], v[10:11], 0, v[122:123]
	v_mul_f32_e32 v17, 0x45800000, v16
	v_cndmask_b32_e32 v16, v16, v17, vcc
	v_pk_mul_f32 v[2:3], v[2:3], v[16:17] op_sel_hi:[1,0]
	v_pk_mul_f32 v[18:19], v[34:35], v[16:17] op_sel_hi:[1,0]
	v_pk_mul_f32 v[4:5], v[4:5], v[16:17] op_sel_hi:[1,0]
	v_pk_mul_f32 v[12:13], v[12:13], v[16:17] op_sel_hi:[1,0]
	v_pk_mul_f32 v[6:7], v[6:7], v[16:17] op_sel_hi:[1,0]
	v_pk_mul_f32 v[14:15], v[14:15], v[16:17] op_sel_hi:[1,0]
	v_pk_mul_f32 v[0:1], v[0:1], v[16:17] op_sel_hi:[1,0]
	v_pk_mul_f32 v[8:9], v[8:9], v[16:17] op_sel_hi:[1,0]
	v_mul_f32_e32 v25, 0xbfb8aa3b, v3
	v_mul_f32_e32 v16, 0xbfb8aa3b, v19
	v_mul_f32_e32 v17, 0xbfb8aa3b, v5
	v_mul_f32_e32 v20, 0xbfb8aa3b, v13
	v_mul_f32_e32 v21, 0xbfb8aa3b, v7
	v_mul_f32_e32 v22, 0xbfb8aa3b, v15
	v_mul_f32_e32 v23, 0xbfb8aa3b, v1
	v_mul_f32_e32 v24, 0xbfb8aa3b, v9
	v_exp_f32_e32 v25, v25
	v_exp_f32_e32 v16, v16
	v_exp_f32_e32 v17, v17
	v_exp_f32_e32 v20, v20
	v_exp_f32_e32 v21, v21
	v_exp_f32_e32 v22, v22
	v_exp_f32_e32 v23, v23
	v_exp_f32_e32 v24, v24
	v_add_f32_e32 v25, 1.0, v25
	v_add_f32_e32 v16, 1.0, v16
	v_add_f32_e32 v17, 1.0, v17
	v_add_f32_e32 v20, 1.0, v20
	v_add_f32_e32 v21, 1.0, v21
	v_add_f32_e32 v22, 1.0, v22
	v_add_f32_e32 v23, 1.0, v23
	v_add_f32_e32 v24, 1.0, v24
	v_rcp_f32_e32 v25, v25
	v_rcp_f32_e32 v16, v16
	v_rcp_f32_e32 v17, v17
	v_rcp_f32_e32 v20, v20
	v_rcp_f32_e32 v21, v21
	v_rcp_f32_e32 v22, v22
	v_rcp_f32_e32 v23, v23
	v_rcp_f32_e32 v24, v24
	v_mul_f32_e32 v3, v3, v25
	v_mul_f32_e32 v16, v19, v16
	v_mul_f32_e32 v5, v5, v17
	v_mul_f32_e32 v13, v13, v20
	v_mul_f32_e32 v7, v7, v21
	v_mul_f32_e32 v15, v15, v22
	v_mul_f32_e32 v1, v1, v23
	v_mul_f32_e32 v9, v9, v24
	v_mul_f32_e32 v3, v2, v3
	s_andn2_b64 vcc, exec, s[4:5]
	s_mov_b64 s[4:5], -1
	v_mul_f32_e32 v16, v18, v16
	v_mul_f32_e32 v4, v4, v5
	v_mul_f32_e32 v5, v12, v13
	v_mul_f32_e32 v6, v6, v7
	v_mul_f32_e32 v7, v14, v15
	v_mul_f32_e32 v12, v0, v1
	v_mul_f32_e32 v8, v8, v9
	v_cvt_pk_bf16_f32 v0, v16, v4
	v_cvt_pk_bf16_f32 v1, v5, v6
	v_cvt_pk_bf16_f32 v2, v7, v12
	v_cvt_pk_bf16_f32 v3, v8, v3
	global_store_dwordx4 v[10:11], v[0:3], off
	s_cbranch_vccnz .LBB0_406
	s_andn2_b64 vcc, exec, s[0:1]
	s_cbranch_vccnz .LBB0_405
	s_barrier
	s_branch .LBB0_405

.LBB0_1712:
	v_lshl_add_u32 v144, s34, 8, v146
	v_ashrrev_i32_e32 v145, 31, v144
	v_lshlrev_b64 v[154:155], 6, v[144:145]
	v_lshl_add_u64 v[166:167], s[18:19], 0, v[154:155]
	global_load_dwordx4 v[154:157], v[166:167], off
	global_load_dwordx4 v[158:161], v[166:167], off offset:16
	global_load_dwordx4 v[162:165], v[166:167], off offset:32
	s_nop 0
	global_load_dwordx4 v[166:169], v[166:167], off offset:48
	v_mov_b32_e32 v174, v122
	v_mov_b32_e32 v175, v114
	v_mov_b32_e32 v114, v123
	v_mov_b32_e32 v172, v124
	v_mov_b32_e32 v173, v116
	v_mov_b32_e32 v116, v125
	v_mov_b32_e32 v124, v126
	v_mov_b32_e32 v125, v118
	v_mov_b32_e32 v118, v127
	v_mov_b32_e32 v127, v112
	v_mov_b32_e32 v112, v121
	v_mov_b32_e32 v126, v120
	v_lshl_or_b32 v170, s79, 7, v148
	v_mov_b64_e32 v[120:121], s[16:17]
	v_ashrrev_i32_e32 v171, 31, v170
	s_waitcnt vmcnt(0)
	v_mov_b32_e32 v122, v155
	v_mov_b32_e32 v123, v156
	v_mov_b32_e32 v155, v157
	v_mov_b32_e32 v156, v159
	v_mov_b32_e32 v157, v160
	v_mov_b32_e32 v159, v161
	v_pk_add_f32 v[122:123], v[122:123], v[154:155]
	v_pk_add_f32 v[154:155], v[156:157], v[158:159]
	v_pk_add_f32 v[122:123], v[122:123], v[122:123] op_sel:[0,1] op_sel_hi:[1,0]
	v_pk_add_f32 v[154:155], v[154:155], v[154:155] op_sel:[0,1] op_sel_hi:[1,0]
	v_add_f32_e32 v160, v162, v163
	v_add_f32_e32 v162, v164, v165
	v_mov_b32_e32 v161, v168
	v_mov_b32_e32 v163, v169
	v_mov_b32_e32 v123, v166
	v_mov_b32_e32 v155, v167
	v_pk_add_f32 v[156:157], v[160:161], v[162:163]
	v_pk_add_f32 v[122:123], v[122:123], v[154:155]
	v_mad_i64_i32 v[154:155], s[36:37], v144, s78, v[120:121]
	v_pk_add_f32 v[122:123], v[122:123], v[156:157]
	s_nop 0
	v_add_f32_e32 v122, v122, v123
	v_or_b32_e32 v252, 16, v144
	v_ashrrev_i32_e32 v253, 31, v252
	v_lshlrev_b64 v[252:253], 6, v[252:253]
	v_lshl_add_u64 v[254:255], s[18:19], 0, v[252:253]
	global_load_dwordx4 v[236:239], v[254:255], off
	global_load_dwordx4 v[240:243], v[254:255], off offset:16
	global_load_dwordx4 v[244:247], v[254:255], off offset:32
	global_load_dwordx4 v[248:251], v[254:255], off offset:48
	v_fmamk_f32 v122, v122, 0x3a800000, v152
	v_mul_f32_e32 v123, 0x4b800000, v122
	v_cmp_gt_f32_e32 vcc, s73, v122
	s_nop 1
	v_cndmask_b32_e32 v122, v122, v123, vcc
	v_rsq_f32_e32 v145, v122
	v_lshlrev_b64 v[122:123], 1, v[170:171]
	v_lshl_add_u64 v[154:155], v[154:155], 0, v[122:123]
	v_mul_f32_e32 v153, 0x45800000, v145
	v_cndmask_b32_e32 v156, v145, v153, vcc
	v_pk_mul_f32 v[158:159], v[172:173], v[156:157] op_sel_hi:[1,0]
	v_pk_mul_f32 v[116:117], v[116:117], v[156:157] op_sel_hi:[1,0]
	v_pk_mul_f32 v[124:125], v[124:125], v[156:157] op_sel_hi:[1,0]
	v_pk_mul_f32 v[118:119], v[118:119], v[156:157] op_sel_hi:[1,0]
	v_pk_mul_f32 v[112:113], v[112:113], v[156:157] op_sel_hi:[1,0]
	v_pk_mul_f32 v[114:115], v[114:115], v[156:157] op_sel_hi:[1,0]
	v_mul_f32_e32 v145, 0xbfb8aa3b, v159
	v_pk_mul_f32 v[126:127], v[126:127], v[156:157] op_sel_hi:[1,0]
	v_pk_mul_f32 v[160:161], v[174:175], v[156:157] op_sel_hi:[1,0]
	v_mul_f32_e32 v153, 0xbfb8aa3b, v117
	v_mul_f32_e32 v156, 0xbfb8aa3b, v125
	v_mul_f32_e32 v157, 0xbfb8aa3b, v119
	v_mul_f32_e32 v163, 0xbfb8aa3b, v113
	v_mul_f32_e32 v165, 0xbfb8aa3b, v115
	v_exp_f32_e32 v145, v145
	v_mul_f32_e32 v162, 0xbfb8aa3b, v127
	v_mul_f32_e32 v164, 0xbfb8aa3b, v161
	v_exp_f32_e32 v153, v153
	v_exp_f32_e32 v156, v156
	v_exp_f32_e32 v157, v157
	v_exp_f32_e32 v163, v163
	v_exp_f32_e32 v165, v165
	v_exp_f32_e32 v162, v162
	v_exp_f32_e32 v164, v164
	v_add_f32_e32 v145, 1.0, v145
	v_add_f32_e32 v153, 1.0, v153
	v_add_f32_e32 v156, 1.0, v156
	v_add_f32_e32 v157, 1.0, v157
	v_add_f32_e32 v163, 1.0, v163
	v_add_f32_e32 v165, 1.0, v165
	v_rcp_f32_e32 v145, v145
	v_add_f32_e32 v162, 1.0, v162
	v_add_f32_e32 v164, 1.0, v164
	v_rcp_f32_e32 v153, v153
	v_rcp_f32_e32 v156, v156
	v_rcp_f32_e32 v157, v157
	v_rcp_f32_e32 v163, v163
	v_rcp_f32_e32 v165, v165
	v_rcp_f32_e32 v162, v162
	v_rcp_f32_e32 v164, v164
	v_mul_f32_e32 v145, v159, v145
	v_mul_f32_e32 v117, v117, v153
	v_mul_f32_e32 v125, v125, v156
	v_mul_f32_e32 v119, v119, v157
	v_mul_f32_e32 v113, v113, v163
	v_mul_f32_e32 v115, v115, v165
	v_mul_f32_e32 v145, v158, v145
	v_or_b32_e32 v158, 16, v144
	v_mul_f32_e32 v127, v127, v162
	v_mul_f32_e32 v153, v161, v164
	v_mul_f32_e32 v116, v116, v117
	v_mul_f32_e32 v117, v124, v125
	v_mul_f32_e32 v118, v118, v119
	v_mul_f32_e32 v124, v112, v113
	v_mul_f32_e32 v115, v114, v115
	v_cvt_pk_bf16_f32 v112, v145, v116
	v_cvt_pk_bf16_f32 v113, v117, v118
	v_ashrrev_i32_e32 v159, 31, v158
	v_mul_f32_e32 v119, v126, v127
	v_mul_f32_e32 v125, v160, v153
	v_cvt_pk_bf16_f32 v114, v119, v124
	v_cvt_pk_bf16_f32 v115, v125, v115
	global_store_dwordx4 v[154:155], v[112:115], off
	v_mov_b32_e32 v160, v108
	v_mov_b32_e32 v161, v100
	v_mov_b32_e32 v100, v109
	v_mov_b32_e32 v108, v110
	v_mov_b32_e32 v109, v102
	v_mov_b32_e32 v102, v111
	v_mov_b32_e32 v110, v104
	v_mov_b32_e32 v111, v96
	v_mov_b32_e32 v96, v105
	v_mov_b32_e32 v104, v106
	v_mov_b32_e32 v105, v98
	v_mov_b32_e32 v98, v107
	s_waitcnt vmcnt(1)
	v_pk_add_f32 v[236:237], v[236:237], v[238:239]
	v_pk_add_f32 v[240:241], v[240:241], v[242:243]
	v_pk_add_f32 v[244:245], v[244:245], v[246:247]
	v_pk_add_f32 v[248:249], v[248:249], v[250:251]
	v_pk_add_f32 v[236:237], v[236:237], v[240:241]
	v_pk_add_f32 v[244:245], v[244:245], v[248:249]
	s_nop 0
	v_pk_add_f32 v[236:237], v[236:237], v[244:245]
	s_nop 0
	v_add_f32_e32 v106, v236, v237
	v_or_b32_e32 v252, 32, v144
	v_ashrrev_i32_e32 v253, 31, v252
	v_lshlrev_b64 v[252:253], 6, v[252:253]
	v_lshl_add_u64 v[254:255], s[18:19], 0, v[252:253]
	global_load_dwordx4 v[236:239], v[254:255], off
	global_load_dwordx4 v[240:243], v[254:255], off offset:16
	global_load_dwordx4 v[244:247], v[254:255], off offset:32
	global_load_dwordx4 v[248:251], v[254:255], off offset:48
	v_fmamk_f32 v106, v106, 0x3a800000, v152
	v_mul_f32_e32 v107, 0x4b800000, v106
	v_cmp_gt_f32_e32 vcc, s73, v106
	s_nop 1
	v_cndmask_b32_e32 v106, v106, v107, vcc
	v_rsq_f32_e32 v112, v106
	v_mad_i64_i32 v[106:107], s[36:37], v158, s78, v[120:121]
	v_lshl_add_u64 v[106:107], v[106:107], 0, v[122:123]
	v_mul_f32_e32 v113, 0x45800000, v112
	v_cndmask_b32_e32 v112, v112, v113, vcc
	v_pk_mul_f32 v[114:115], v[160:161], v[112:113] op_sel_hi:[1,0]
	v_pk_mul_f32 v[100:101], v[100:101], v[112:113] op_sel_hi:[1,0]
	v_pk_mul_f32 v[108:109], v[108:109], v[112:113] op_sel_hi:[1,0]
	v_pk_mul_f32 v[102:103], v[102:103], v[112:113] op_sel_hi:[1,0]
	v_pk_mul_f32 v[110:111], v[110:111], v[112:113] op_sel_hi:[1,0]
	v_pk_mul_f32 v[96:97], v[96:97], v[112:113] op_sel_hi:[1,0]
	v_pk_mul_f32 v[104:105], v[104:105], v[112:113] op_sel_hi:[1,0]
	v_pk_mul_f32 v[98:99], v[98:99], v[112:113] op_sel_hi:[1,0]
	v_mul_f32_e32 v112, 0xbfb8aa3b, v115
	v_mul_f32_e32 v113, 0xbfb8aa3b, v101
	v_mul_f32_e32 v116, 0xbfb8aa3b, v109
	v_mul_f32_e32 v119, 0xbfb8aa3b, v97
	v_exp_f32_e32 v112, v112
	v_mul_f32_e32 v117, 0xbfb8aa3b, v103
	v_mul_f32_e32 v125, 0xbfb8aa3b, v99
	v_exp_f32_e32 v113, v113
	v_exp_f32_e32 v116, v116
	v_exp_f32_e32 v119, v119
	v_mul_f32_e32 v118, 0xbfb8aa3b, v111
	v_mul_f32_e32 v124, 0xbfb8aa3b, v105
	v_exp_f32_e32 v117, v117
	v_exp_f32_e32 v125, v125
	v_exp_f32_e32 v118, v118
	v_exp_f32_e32 v124, v124
	v_add_f32_e32 v112, 1.0, v112
	v_add_f32_e32 v113, 1.0, v113
	v_add_f32_e32 v116, 1.0, v116
	v_add_f32_e32 v119, 1.0, v119
	v_rcp_f32_e32 v112, v112
	v_add_f32_e32 v117, 1.0, v117
	v_add_f32_e32 v125, 1.0, v125
	v_rcp_f32_e32 v113, v113
	v_rcp_f32_e32 v116, v116
	v_rcp_f32_e32 v119, v119
	v_add_f32_e32 v118, 1.0, v118
	v_add_f32_e32 v124, 1.0, v124
	v_rcp_f32_e32 v117, v117
	v_rcp_f32_e32 v125, v125
	v_rcp_f32_e32 v118, v118
	v_rcp_f32_e32 v124, v124
	v_mul_f32_e32 v112, v115, v112
	v_mul_f32_e32 v101, v101, v113
	v_mul_f32_e32 v109, v109, v116
	v_mul_f32_e32 v97, v97, v119
	v_mul_f32_e32 v112, v114, v112
	v_mul_f32_e32 v103, v103, v117
	v_mul_f32_e32 v99, v99, v125
	v_mul_f32_e32 v100, v100, v101
	v_mul_f32_e32 v101, v108, v109
	v_mul_f32_e32 v108, v96, v97
	v_cvt_pk_bf16_f32 v96, v112, v100
	v_or_b32_e32 v112, 32, v144
	v_mul_f32_e32 v111, v111, v118
	v_mul_f32_e32 v105, v105, v124
	v_mul_f32_e32 v102, v102, v103
	v_mul_f32_e32 v99, v98, v99
	v_cvt_pk_bf16_f32 v97, v101, v102
	v_ashrrev_i32_e32 v113, 31, v112
	v_mul_f32_e32 v103, v110, v111
	v_mul_f32_e32 v104, v104, v105
	v_cvt_pk_bf16_f32 v98, v103, v108
	v_cvt_pk_bf16_f32 v99, v104, v99
	global_store_dwordx4 v[106:107], v[96:99], off
	v_mov_b32_e32 v114, v92
	v_mov_b32_e32 v115, v84
	v_mov_b32_e32 v84, v93
	v_mov_b32_e32 v92, v94
	v_mov_b32_e32 v93, v86
	v_mov_b32_e32 v86, v95
	v_mov_b32_e32 v94, v88
	v_mov_b32_e32 v95, v80
	v_mov_b32_e32 v80, v89
	v_mov_b32_e32 v88, v90
	v_mov_b32_e32 v89, v82
	v_mov_b32_e32 v82, v91
	s_waitcnt vmcnt(1)
	v_pk_add_f32 v[236:237], v[236:237], v[238:239]
	v_pk_add_f32 v[240:241], v[240:241], v[242:243]
	v_pk_add_f32 v[244:245], v[244:245], v[246:247]
	v_pk_add_f32 v[248:249], v[248:249], v[250:251]
	v_pk_add_f32 v[236:237], v[236:237], v[240:241]
	v_pk_add_f32 v[244:245], v[244:245], v[248:249]
	s_nop 0
	v_pk_add_f32 v[236:237], v[236:237], v[244:245]
	s_nop 0
	v_add_f32_e32 v90, v236, v237
	v_or_b32_e32 v252, 48, v144
	v_ashrrev_i32_e32 v253, 31, v252
	v_lshlrev_b64 v[252:253], 6, v[252:253]
	v_lshl_add_u64 v[254:255], s[18:19], 0, v[252:253]
	global_load_dwordx4 v[236:239], v[254:255], off
	global_load_dwordx4 v[240:243], v[254:255], off offset:16
	global_load_dwordx4 v[244:247], v[254:255], off offset:32
	global_load_dwordx4 v[248:251], v[254:255], off offset:48
	v_fmamk_f32 v90, v90, 0x3a800000, v152
	v_mul_f32_e32 v91, 0x4b800000, v90
	v_cmp_gt_f32_e32 vcc, s73, v90
	s_nop 1
	v_cndmask_b32_e32 v90, v90, v91, vcc
	v_rsq_f32_e32 v96, v90
	v_mad_i64_i32 v[90:91], s[36:37], v112, s78, v[120:121]
	v_lshl_add_u64 v[90:91], v[90:91], 0, v[122:123]
	v_mul_f32_e32 v97, 0x45800000, v96
	v_cndmask_b32_e32 v96, v96, v97, vcc
	v_pk_mul_f32 v[98:99], v[114:115], v[96:97] op_sel_hi:[1,0]
	v_pk_mul_f32 v[84:85], v[84:85], v[96:97] op_sel_hi:[1,0]
	v_pk_mul_f32 v[92:93], v[92:93], v[96:97] op_sel_hi:[1,0]
	v_pk_mul_f32 v[86:87], v[86:87], v[96:97] op_sel_hi:[1,0]
	v_pk_mul_f32 v[94:95], v[94:95], v[96:97] op_sel_hi:[1,0]
	v_pk_mul_f32 v[80:81], v[80:81], v[96:97] op_sel_hi:[1,0]
	v_pk_mul_f32 v[88:89], v[88:89], v[96:97] op_sel_hi:[1,0]
	v_pk_mul_f32 v[82:83], v[82:83], v[96:97] op_sel_hi:[1,0]
	v_mul_f32_e32 v96, 0xbfb8aa3b, v99
	v_mul_f32_e32 v97, 0xbfb8aa3b, v85
	v_mul_f32_e32 v100, 0xbfb8aa3b, v93
	v_mul_f32_e32 v103, 0xbfb8aa3b, v81
	v_exp_f32_e32 v96, v96
	v_mul_f32_e32 v101, 0xbfb8aa3b, v87
	v_mul_f32_e32 v105, 0xbfb8aa3b, v83
	v_exp_f32_e32 v97, v97
	v_exp_f32_e32 v100, v100
	v_exp_f32_e32 v103, v103
	v_mul_f32_e32 v102, 0xbfb8aa3b, v95
	v_mul_f32_e32 v104, 0xbfb8aa3b, v89
	v_exp_f32_e32 v101, v101
	v_exp_f32_e32 v105, v105
	v_exp_f32_e32 v102, v102
	v_exp_f32_e32 v104, v104
	v_add_f32_e32 v96, 1.0, v96
	v_add_f32_e32 v97, 1.0, v97
	v_add_f32_e32 v100, 1.0, v100
	v_add_f32_e32 v103, 1.0, v103
	v_rcp_f32_e32 v96, v96
	v_add_f32_e32 v101, 1.0, v101
	v_add_f32_e32 v105, 1.0, v105
	v_rcp_f32_e32 v97, v97
	v_rcp_f32_e32 v100, v100
	v_rcp_f32_e32 v103, v103
	v_add_f32_e32 v102, 1.0, v102
	v_add_f32_e32 v104, 1.0, v104
	v_rcp_f32_e32 v101, v101
	v_rcp_f32_e32 v105, v105
	v_rcp_f32_e32 v102, v102
	v_rcp_f32_e32 v104, v104
	v_mul_f32_e32 v96, v99, v96
	v_mul_f32_e32 v85, v85, v97
	v_mul_f32_e32 v93, v93, v100
	v_mul_f32_e32 v81, v81, v103
	v_mul_f32_e32 v96, v98, v96
	v_mul_f32_e32 v87, v87, v101
	v_mul_f32_e32 v83, v83, v105
	v_mul_f32_e32 v84, v84, v85
	v_mul_f32_e32 v85, v92, v93
	v_mul_f32_e32 v92, v80, v81
	v_cvt_pk_bf16_f32 v80, v96, v84
	v_or_b32_e32 v96, 48, v144
	v_mul_f32_e32 v95, v95, v102
	v_mul_f32_e32 v89, v89, v104
	v_mul_f32_e32 v86, v86, v87
	v_mul_f32_e32 v83, v82, v83
	v_cvt_pk_bf16_f32 v81, v85, v86
	v_ashrrev_i32_e32 v97, 31, v96
	v_mul_f32_e32 v87, v94, v95
	v_mul_f32_e32 v88, v88, v89
	v_cvt_pk_bf16_f32 v82, v87, v92
	v_cvt_pk_bf16_f32 v83, v88, v83
	global_store_dwordx4 v[90:91], v[80:83], off
	v_mov_b32_e32 v98, v76
	v_mov_b32_e32 v99, v68
	v_mov_b32_e32 v68, v77
	v_mov_b32_e32 v76, v78
	v_mov_b32_e32 v77, v70
	v_mov_b32_e32 v70, v79
	v_mov_b32_e32 v78, v72
	v_mov_b32_e32 v79, v64
	v_mov_b32_e32 v64, v73
	v_mov_b32_e32 v72, v74
	v_mov_b32_e32 v73, v66
	v_mov_b32_e32 v66, v75
	s_waitcnt vmcnt(1)
	v_pk_add_f32 v[236:237], v[236:237], v[238:239]
	v_pk_add_f32 v[240:241], v[240:241], v[242:243]
	v_pk_add_f32 v[244:245], v[244:245], v[246:247]
	v_pk_add_f32 v[248:249], v[248:249], v[250:251]
	v_pk_add_f32 v[236:237], v[236:237], v[240:241]
	v_pk_add_f32 v[244:245], v[244:245], v[248:249]
	s_nop 0
	v_pk_add_f32 v[236:237], v[236:237], v[244:245]
	s_nop 0
	v_add_f32_e32 v74, v236, v237
	v_add_u32_e32 v252, 0x80, v144
	v_ashrrev_i32_e32 v253, 31, v252
	v_lshlrev_b64 v[252:253], 6, v[252:253]
	v_lshl_add_u64 v[254:255], s[18:19], 0, v[252:253]
	global_load_dwordx4 v[236:239], v[254:255], off
	global_load_dwordx4 v[240:243], v[254:255], off offset:16
	global_load_dwordx4 v[244:247], v[254:255], off offset:32
	global_load_dwordx4 v[248:251], v[254:255], off offset:48
	v_fmamk_f32 v74, v74, 0x3a800000, v152
	v_mul_f32_e32 v75, 0x4b800000, v74
	v_cmp_gt_f32_e32 vcc, s73, v74
	s_nop 1
	v_cndmask_b32_e32 v74, v74, v75, vcc
	v_rsq_f32_e32 v80, v74
	v_mad_i64_i32 v[74:75], s[36:37], v96, s78, v[120:121]
	v_lshl_add_u64 v[74:75], v[74:75], 0, v[122:123]
	v_mul_f32_e32 v81, 0x45800000, v80
	v_cndmask_b32_e32 v80, v80, v81, vcc
	v_pk_mul_f32 v[82:83], v[98:99], v[80:81] op_sel_hi:[1,0]
	v_pk_mul_f32 v[68:69], v[68:69], v[80:81] op_sel_hi:[1,0]
	v_pk_mul_f32 v[76:77], v[76:77], v[80:81] op_sel_hi:[1,0]
	v_pk_mul_f32 v[70:71], v[70:71], v[80:81] op_sel_hi:[1,0]
	v_pk_mul_f32 v[78:79], v[78:79], v[80:81] op_sel_hi:[1,0]
	v_pk_mul_f32 v[64:65], v[64:65], v[80:81] op_sel_hi:[1,0]
	v_pk_mul_f32 v[72:73], v[72:73], v[80:81] op_sel_hi:[1,0]
	v_pk_mul_f32 v[66:67], v[66:67], v[80:81] op_sel_hi:[1,0]
	v_mul_f32_e32 v80, 0xbfb8aa3b, v83
	v_mul_f32_e32 v81, 0xbfb8aa3b, v69
	v_mul_f32_e32 v84, 0xbfb8aa3b, v77
	v_mul_f32_e32 v87, 0xbfb8aa3b, v65
	v_exp_f32_e32 v80, v80
	v_mul_f32_e32 v85, 0xbfb8aa3b, v71
	v_mul_f32_e32 v89, 0xbfb8aa3b, v67
	v_exp_f32_e32 v81, v81
	v_exp_f32_e32 v84, v84
	v_exp_f32_e32 v87, v87
	v_mul_f32_e32 v86, 0xbfb8aa3b, v79
	v_mul_f32_e32 v88, 0xbfb8aa3b, v73
	v_exp_f32_e32 v85, v85
	v_exp_f32_e32 v89, v89
	v_exp_f32_e32 v86, v86
	v_exp_f32_e32 v88, v88
	v_add_f32_e32 v80, 1.0, v80
	v_add_f32_e32 v81, 1.0, v81
	v_add_f32_e32 v84, 1.0, v84
	v_add_f32_e32 v87, 1.0, v87
	v_rcp_f32_e32 v80, v80
	v_add_f32_e32 v85, 1.0, v85
	v_add_f32_e32 v89, 1.0, v89
	v_rcp_f32_e32 v81, v81
	v_rcp_f32_e32 v84, v84
	v_rcp_f32_e32 v87, v87
	v_add_f32_e32 v86, 1.0, v86
	v_add_f32_e32 v88, 1.0, v88
	v_rcp_f32_e32 v85, v85
	v_rcp_f32_e32 v89, v89
	v_rcp_f32_e32 v86, v86
	v_rcp_f32_e32 v88, v88
	v_mul_f32_e32 v80, v83, v80
	v_mul_f32_e32 v69, v69, v81
	v_mul_f32_e32 v77, v77, v84
	v_mul_f32_e32 v65, v65, v87
	v_mul_f32_e32 v80, v82, v80
	v_mul_f32_e32 v71, v71, v85
	v_mul_f32_e32 v67, v67, v89
	v_mul_f32_e32 v68, v68, v69
	v_mul_f32_e32 v69, v76, v77
	v_mul_f32_e32 v76, v64, v65
	v_cvt_pk_bf16_f32 v64, v80, v68
	v_add_u32_e32 v80, 0x80, v144
	v_mul_f32_e32 v79, v79, v86
	v_mul_f32_e32 v73, v73, v88
	v_mul_f32_e32 v70, v70, v71
	v_mul_f32_e32 v67, v66, v67
	v_cvt_pk_bf16_f32 v65, v69, v70
	v_ashrrev_i32_e32 v81, 31, v80
	v_mul_f32_e32 v71, v78, v79
	v_mul_f32_e32 v72, v72, v73
	v_cvt_pk_bf16_f32 v66, v71, v76
	v_cvt_pk_bf16_f32 v67, v72, v67
	global_store_dwordx4 v[74:75], v[64:67], off
	v_mov_b32_e32 v82, v60
	v_mov_b32_e32 v83, v52
	v_mov_b32_e32 v52, v61
	v_mov_b32_e32 v60, v62
	v_mov_b32_e32 v61, v54
	v_mov_b32_e32 v54, v63
	v_mov_b32_e32 v62, v56
	v_mov_b32_e32 v63, v48
	v_mov_b32_e32 v48, v57
	v_mov_b32_e32 v56, v58
	v_mov_b32_e32 v57, v50
	v_mov_b32_e32 v50, v59
	s_waitcnt vmcnt(1)
	v_pk_add_f32 v[236:237], v[236:237], v[238:239]
	v_pk_add_f32 v[240:241], v[240:241], v[242:243]
	v_pk_add_f32 v[244:245], v[244:245], v[246:247]
	v_pk_add_f32 v[248:249], v[248:249], v[250:251]
	v_pk_add_f32 v[236:237], v[236:237], v[240:241]
	v_pk_add_f32 v[244:245], v[244:245], v[248:249]
	s_nop 0
	v_pk_add_f32 v[236:237], v[236:237], v[244:245]
	s_nop 0
	v_add_f32_e32 v58, v236, v237
	v_add_u32_e32 v252, 0x90, v144
	v_ashrrev_i32_e32 v253, 31, v252
	v_lshlrev_b64 v[252:253], 6, v[252:253]
	v_lshl_add_u64 v[254:255], s[18:19], 0, v[252:253]
	global_load_dwordx4 v[236:239], v[254:255], off
	global_load_dwordx4 v[240:243], v[254:255], off offset:16
	global_load_dwordx4 v[244:247], v[254:255], off offset:32
	global_load_dwordx4 v[248:251], v[254:255], off offset:48
	v_fmamk_f32 v58, v58, 0x3a800000, v152
	v_mul_f32_e32 v59, 0x4b800000, v58
	v_cmp_gt_f32_e32 vcc, s73, v58
	s_nop 1
	v_cndmask_b32_e32 v58, v58, v59, vcc
	v_rsq_f32_e32 v64, v58
	v_mad_i64_i32 v[58:59], s[36:37], v80, s78, v[120:121]
	v_lshl_add_u64 v[58:59], v[58:59], 0, v[122:123]
	v_mul_f32_e32 v65, 0x45800000, v64
	v_cndmask_b32_e32 v64, v64, v65, vcc
	v_pk_mul_f32 v[66:67], v[82:83], v[64:65] op_sel_hi:[1,0]
	v_pk_mul_f32 v[52:53], v[52:53], v[64:65] op_sel_hi:[1,0]
	v_pk_mul_f32 v[60:61], v[60:61], v[64:65] op_sel_hi:[1,0]
	v_pk_mul_f32 v[54:55], v[54:55], v[64:65] op_sel_hi:[1,0]
	v_pk_mul_f32 v[62:63], v[62:63], v[64:65] op_sel_hi:[1,0]
	v_pk_mul_f32 v[48:49], v[48:49], v[64:65] op_sel_hi:[1,0]
	v_pk_mul_f32 v[56:57], v[56:57], v[64:65] op_sel_hi:[1,0]
	v_pk_mul_f32 v[50:51], v[50:51], v[64:65] op_sel_hi:[1,0]
	v_mul_f32_e32 v64, 0xbfb8aa3b, v67
	v_mul_f32_e32 v65, 0xbfb8aa3b, v53
	v_mul_f32_e32 v68, 0xbfb8aa3b, v61
	v_mul_f32_e32 v71, 0xbfb8aa3b, v49
	v_exp_f32_e32 v64, v64
	v_mul_f32_e32 v69, 0xbfb8aa3b, v55
	v_mul_f32_e32 v73, 0xbfb8aa3b, v51
	v_exp_f32_e32 v65, v65
	v_exp_f32_e32 v68, v68
	v_exp_f32_e32 v71, v71
	v_mul_f32_e32 v70, 0xbfb8aa3b, v63
	v_mul_f32_e32 v72, 0xbfb8aa3b, v57
	v_exp_f32_e32 v69, v69
	v_exp_f32_e32 v73, v73
	v_exp_f32_e32 v70, v70
	v_exp_f32_e32 v72, v72
	v_add_f32_e32 v64, 1.0, v64
	v_add_f32_e32 v65, 1.0, v65
	v_add_f32_e32 v68, 1.0, v68
	v_add_f32_e32 v71, 1.0, v71
	v_rcp_f32_e32 v64, v64
	v_add_f32_e32 v69, 1.0, v69
	v_add_f32_e32 v73, 1.0, v73
	v_rcp_f32_e32 v65, v65
	v_rcp_f32_e32 v68, v68
	v_rcp_f32_e32 v71, v71
	v_add_f32_e32 v70, 1.0, v70
	v_add_f32_e32 v72, 1.0, v72
	v_rcp_f32_e32 v69, v69
	v_rcp_f32_e32 v73, v73
	v_rcp_f32_e32 v70, v70
	v_rcp_f32_e32 v72, v72
	v_mul_f32_e32 v64, v67, v64
	v_mul_f32_e32 v53, v53, v65
	v_mul_f32_e32 v61, v61, v68
	v_mul_f32_e32 v49, v49, v71
	v_mul_f32_e32 v64, v66, v64
	v_mul_f32_e32 v55, v55, v69
	v_mul_f32_e32 v51, v51, v73
	v_mul_f32_e32 v52, v52, v53
	v_mul_f32_e32 v53, v60, v61
	v_mul_f32_e32 v60, v48, v49
	v_cvt_pk_bf16_f32 v48, v64, v52
	v_add_u32_e32 v64, 0x90, v144
	v_mul_f32_e32 v63, v63, v70
	v_mul_f32_e32 v57, v57, v72
	v_mul_f32_e32 v54, v54, v55
	v_mul_f32_e32 v51, v50, v51
	v_cvt_pk_bf16_f32 v49, v53, v54
	v_ashrrev_i32_e32 v65, 31, v64
	v_mul_f32_e32 v55, v62, v63
	v_mul_f32_e32 v56, v56, v57
	v_cvt_pk_bf16_f32 v50, v55, v60
	v_cvt_pk_bf16_f32 v51, v56, v51
	global_store_dwordx4 v[58:59], v[48:51], off
	v_mov_b32_e32 v66, v44
	v_mov_b32_e32 v67, v36
	v_mov_b32_e32 v36, v45
	v_mov_b32_e32 v44, v46
	v_mov_b32_e32 v45, v38
	v_mov_b32_e32 v38, v47
	v_mov_b32_e32 v46, v40
	v_mov_b32_e32 v47, v32
	v_mov_b32_e32 v32, v41
	v_mov_b32_e32 v40, v42
	v_mov_b32_e32 v41, v34
	v_mov_b32_e32 v34, v43
	s_waitcnt vmcnt(1)
	v_pk_add_f32 v[236:237], v[236:237], v[238:239]
	v_pk_add_f32 v[240:241], v[240:241], v[242:243]
	v_pk_add_f32 v[244:245], v[244:245], v[246:247]
	v_pk_add_f32 v[248:249], v[248:249], v[250:251]
	v_pk_add_f32 v[236:237], v[236:237], v[240:241]
	v_pk_add_f32 v[244:245], v[244:245], v[248:249]
	s_nop 0
	v_pk_add_f32 v[236:237], v[236:237], v[244:245]
	s_nop 0
	v_add_f32_e32 v42, v236, v237
	v_add_u32_e32 v252, 0xa0, v144
	v_ashrrev_i32_e32 v253, 31, v252
	v_lshlrev_b64 v[252:253], 6, v[252:253]
	v_lshl_add_u64 v[254:255], s[18:19], 0, v[252:253]
	global_load_dwordx4 v[236:239], v[254:255], off
	global_load_dwordx4 v[240:243], v[254:255], off offset:16
	global_load_dwordx4 v[244:247], v[254:255], off offset:32
	global_load_dwordx4 v[248:251], v[254:255], off offset:48
	v_fmamk_f32 v42, v42, 0x3a800000, v152
	v_mul_f32_e32 v43, 0x4b800000, v42
	v_cmp_gt_f32_e32 vcc, s73, v42
	s_nop 1
	v_cndmask_b32_e32 v42, v42, v43, vcc
	v_rsq_f32_e32 v48, v42
	v_mad_i64_i32 v[42:43], s[36:37], v64, s78, v[120:121]
	v_lshl_add_u64 v[42:43], v[42:43], 0, v[122:123]
	v_mul_f32_e32 v49, 0x45800000, v48
	v_cndmask_b32_e32 v48, v48, v49, vcc
	v_pk_mul_f32 v[50:51], v[66:67], v[48:49] op_sel_hi:[1,0]
	v_pk_mul_f32 v[36:37], v[36:37], v[48:49] op_sel_hi:[1,0]
	v_pk_mul_f32 v[44:45], v[44:45], v[48:49] op_sel_hi:[1,0]
	v_pk_mul_f32 v[38:39], v[38:39], v[48:49] op_sel_hi:[1,0]
	v_pk_mul_f32 v[46:47], v[46:47], v[48:49] op_sel_hi:[1,0]
	v_pk_mul_f32 v[32:33], v[32:33], v[48:49] op_sel_hi:[1,0]
	v_pk_mul_f32 v[40:41], v[40:41], v[48:49] op_sel_hi:[1,0]
	v_pk_mul_f32 v[34:35], v[34:35], v[48:49] op_sel_hi:[1,0]
	v_mul_f32_e32 v48, 0xbfb8aa3b, v51
	v_mul_f32_e32 v49, 0xbfb8aa3b, v37
	v_mul_f32_e32 v52, 0xbfb8aa3b, v45
	v_mul_f32_e32 v55, 0xbfb8aa3b, v33
	v_exp_f32_e32 v48, v48
	v_mul_f32_e32 v53, 0xbfb8aa3b, v39
	v_mul_f32_e32 v57, 0xbfb8aa3b, v35
	v_exp_f32_e32 v49, v49
	v_exp_f32_e32 v52, v52
	v_exp_f32_e32 v55, v55
	v_mul_f32_e32 v54, 0xbfb8aa3b, v47
	v_mul_f32_e32 v56, 0xbfb8aa3b, v41
	v_exp_f32_e32 v53, v53
	v_exp_f32_e32 v57, v57
	v_exp_f32_e32 v54, v54
	v_exp_f32_e32 v56, v56
	v_add_f32_e32 v48, 1.0, v48
	v_add_f32_e32 v49, 1.0, v49
	v_add_f32_e32 v52, 1.0, v52
	v_add_f32_e32 v55, 1.0, v55
	v_rcp_f32_e32 v48, v48
	v_add_f32_e32 v53, 1.0, v53
	v_add_f32_e32 v57, 1.0, v57
	v_rcp_f32_e32 v49, v49
	v_rcp_f32_e32 v52, v52
	v_rcp_f32_e32 v55, v55
	v_add_f32_e32 v54, 1.0, v54
	v_add_f32_e32 v56, 1.0, v56
	v_rcp_f32_e32 v53, v53
	v_rcp_f32_e32 v57, v57
	v_rcp_f32_e32 v54, v54
	v_rcp_f32_e32 v56, v56
	v_mul_f32_e32 v48, v51, v48
	v_mul_f32_e32 v37, v37, v49
	v_mul_f32_e32 v45, v45, v52
	v_mul_f32_e32 v33, v33, v55
	v_mul_f32_e32 v48, v50, v48
	v_mul_f32_e32 v39, v39, v53
	v_mul_f32_e32 v35, v35, v57
	v_mul_f32_e32 v36, v36, v37
	v_mul_f32_e32 v37, v44, v45
	v_mul_f32_e32 v44, v32, v33
	v_cvt_pk_bf16_f32 v32, v48, v36
	v_add_u32_e32 v48, 0xa0, v144
	v_mul_f32_e32 v47, v47, v54
	v_mul_f32_e32 v41, v41, v56
	v_mul_f32_e32 v38, v38, v39
	v_mul_f32_e32 v35, v34, v35
	v_cvt_pk_bf16_f32 v33, v37, v38
	v_ashrrev_i32_e32 v49, 31, v48
	v_mul_f32_e32 v39, v46, v47
	v_mul_f32_e32 v40, v40, v41
	v_cvt_pk_bf16_f32 v34, v39, v44
	v_cvt_pk_bf16_f32 v35, v40, v35
	global_store_dwordx4 v[42:43], v[32:35], off
	v_mov_b32_e32 v50, v28
	v_mov_b32_e32 v51, v20
	v_mov_b32_e32 v20, v29
	v_mov_b32_e32 v28, v30
	v_mov_b32_e32 v29, v22
	v_mov_b32_e32 v22, v31
	v_mov_b32_e32 v30, v24
	v_mov_b32_e32 v31, v16
	v_mov_b32_e32 v16, v25
	v_mov_b32_e32 v24, v26
	v_mov_b32_e32 v25, v18
	v_mov_b32_e32 v18, v27
	s_waitcnt vmcnt(1)
	v_pk_add_f32 v[236:237], v[236:237], v[238:239]
	v_pk_add_f32 v[240:241], v[240:241], v[242:243]
	v_pk_add_f32 v[244:245], v[244:245], v[246:247]
	v_pk_add_f32 v[248:249], v[248:249], v[250:251]
	v_pk_add_f32 v[236:237], v[236:237], v[240:241]
	v_pk_add_f32 v[244:245], v[244:245], v[248:249]
	s_nop 0
	v_pk_add_f32 v[236:237], v[236:237], v[244:245]
	s_nop 0
	v_add_f32_e32 v26, v236, v237
	v_add_u32_e32 v252, 0xb0, v144
	v_ashrrev_i32_e32 v253, 31, v252
	v_lshlrev_b64 v[252:253], 6, v[252:253]
	v_lshl_add_u64 v[254:255], s[18:19], 0, v[252:253]
	global_load_dwordx4 v[236:239], v[254:255], off
	global_load_dwordx4 v[240:243], v[254:255], off offset:16
	global_load_dwordx4 v[244:247], v[254:255], off offset:32
	global_load_dwordx4 v[248:251], v[254:255], off offset:48
	v_fmamk_f32 v26, v26, 0x3a800000, v152
	v_mul_f32_e32 v27, 0x4b800000, v26
	v_cmp_gt_f32_e32 vcc, s73, v26
	s_nop 1
	v_cndmask_b32_e32 v26, v26, v27, vcc
	v_rsq_f32_e32 v32, v26
	v_mad_i64_i32 v[26:27], s[36:37], v48, s78, v[120:121]
	v_lshl_add_u64 v[26:27], v[26:27], 0, v[122:123]
	v_mul_f32_e32 v33, 0x45800000, v32
	v_cndmask_b32_e32 v32, v32, v33, vcc
	v_pk_mul_f32 v[34:35], v[50:51], v[32:33] op_sel_hi:[1,0]
	v_pk_mul_f32 v[20:21], v[20:21], v[32:33] op_sel_hi:[1,0]
	v_pk_mul_f32 v[28:29], v[28:29], v[32:33] op_sel_hi:[1,0]
	v_pk_mul_f32 v[22:23], v[22:23], v[32:33] op_sel_hi:[1,0]
	v_pk_mul_f32 v[30:31], v[30:31], v[32:33] op_sel_hi:[1,0]
	v_pk_mul_f32 v[16:17], v[16:17], v[32:33] op_sel_hi:[1,0]
	v_pk_mul_f32 v[24:25], v[24:25], v[32:33] op_sel_hi:[1,0]
	v_pk_mul_f32 v[18:19], v[18:19], v[32:33] op_sel_hi:[1,0]
	v_mul_f32_e32 v32, 0xbfb8aa3b, v35
	v_mul_f32_e32 v33, 0xbfb8aa3b, v21
	v_mul_f32_e32 v36, 0xbfb8aa3b, v29
	v_mul_f32_e32 v39, 0xbfb8aa3b, v17
	v_exp_f32_e32 v32, v32
	v_mul_f32_e32 v37, 0xbfb8aa3b, v23
	v_mul_f32_e32 v41, 0xbfb8aa3b, v19
	v_exp_f32_e32 v33, v33
	v_exp_f32_e32 v36, v36
	v_exp_f32_e32 v39, v39
	v_mul_f32_e32 v38, 0xbfb8aa3b, v31
	v_mul_f32_e32 v40, 0xbfb8aa3b, v25
	v_exp_f32_e32 v37, v37
	v_exp_f32_e32 v41, v41
	v_exp_f32_e32 v38, v38
	v_exp_f32_e32 v40, v40
	v_add_f32_e32 v32, 1.0, v32
	v_add_f32_e32 v33, 1.0, v33
	v_add_f32_e32 v36, 1.0, v36
	v_add_f32_e32 v39, 1.0, v39
	v_rcp_f32_e32 v32, v32
	v_add_f32_e32 v37, 1.0, v37
	v_add_f32_e32 v41, 1.0, v41
	v_rcp_f32_e32 v33, v33
	v_rcp_f32_e32 v36, v36
	v_rcp_f32_e32 v39, v39
	v_add_f32_e32 v38, 1.0, v38
	v_add_f32_e32 v40, 1.0, v40
	v_rcp_f32_e32 v37, v37
	v_rcp_f32_e32 v41, v41
	v_rcp_f32_e32 v38, v38
	v_rcp_f32_e32 v40, v40
	v_mul_f32_e32 v32, v35, v32
	v_mul_f32_e32 v21, v21, v33
	v_mul_f32_e32 v29, v29, v36
	v_mul_f32_e32 v17, v17, v39
	v_mul_f32_e32 v32, v34, v32
	v_mul_f32_e32 v23, v23, v37
	v_mul_f32_e32 v19, v19, v41
	v_mul_f32_e32 v20, v20, v21
	v_mul_f32_e32 v21, v28, v29
	v_mul_f32_e32 v28, v16, v17
	v_cvt_pk_bf16_f32 v16, v32, v20
	v_add_u32_e32 v32, 0xb0, v144
	v_mul_f32_e32 v31, v31, v38
	v_mul_f32_e32 v25, v25, v40
	v_mul_f32_e32 v22, v22, v23
	v_mul_f32_e32 v19, v18, v19
	v_cvt_pk_bf16_f32 v17, v21, v22
	v_ashrrev_i32_e32 v33, 31, v32
	v_mul_f32_e32 v23, v30, v31
	v_mul_f32_e32 v24, v24, v25
	v_cvt_pk_bf16_f32 v18, v23, v28
	v_cvt_pk_bf16_f32 v19, v24, v19
	global_store_dwordx4 v[26:27], v[16:19], off
	v_mov_b32_e32 v34, v12
	v_mov_b32_e32 v35, v4
	v_mov_b32_e32 v4, v13
	v_mov_b32_e32 v12, v14
	v_mov_b32_e32 v13, v6
	v_mov_b32_e32 v6, v15
	v_mov_b32_e32 v14, v8
	v_mov_b32_e32 v15, v0
	v_mov_b32_e32 v0, v9
	v_mov_b32_e32 v8, v10
	v_mov_b32_e32 v9, v2
	v_mov_b32_e32 v2, v11
	s_waitcnt vmcnt(1)
	v_pk_add_f32 v[236:237], v[236:237], v[238:239]
	v_pk_add_f32 v[240:241], v[240:241], v[242:243]
	v_pk_add_f32 v[244:245], v[244:245], v[246:247]
	v_pk_add_f32 v[248:249], v[248:249], v[250:251]
	v_pk_add_f32 v[236:237], v[236:237], v[240:241]
	v_pk_add_f32 v[244:245], v[244:245], v[248:249]
	s_nop 0
	v_pk_add_f32 v[236:237], v[236:237], v[244:245]
	s_nop 0
	v_add_f32_e32 v10, v236, v237
	v_fmamk_f32 v10, v10, 0x3a800000, v152
	v_mul_f32_e32 v11, 0x4b800000, v10
	v_cmp_gt_f32_e32 vcc, s73, v10
	s_nop 1
	v_cndmask_b32_e32 v10, v10, v11, vcc
	v_rsq_f32_e32 v16, v10
	v_mad_i64_i32 v[10:11], s[36:37], v32, s78, v[120:121]
	v_lshl_add_u64 v[10:11], v[10:11], 0, v[122:123]
	v_mul_f32_e32 v17, 0x45800000, v16
	v_cndmask_b32_e32 v16, v16, v17, vcc
	v_pk_mul_f32 v[2:3], v[2:3], v[16:17] op_sel_hi:[1,0]
	v_pk_mul_f32 v[18:19], v[34:35], v[16:17] op_sel_hi:[1,0]
	v_pk_mul_f32 v[4:5], v[4:5], v[16:17] op_sel_hi:[1,0]
	v_pk_mul_f32 v[12:13], v[12:13], v[16:17] op_sel_hi:[1,0]
	v_pk_mul_f32 v[6:7], v[6:7], v[16:17] op_sel_hi:[1,0]
	v_pk_mul_f32 v[14:15], v[14:15], v[16:17] op_sel_hi:[1,0]
	v_pk_mul_f32 v[0:1], v[0:1], v[16:17] op_sel_hi:[1,0]
	v_pk_mul_f32 v[8:9], v[8:9], v[16:17] op_sel_hi:[1,0]
	v_mul_f32_e32 v25, 0xbfb8aa3b, v3
	v_mul_f32_e32 v16, 0xbfb8aa3b, v19
	v_mul_f32_e32 v17, 0xbfb8aa3b, v5
	v_mul_f32_e32 v20, 0xbfb8aa3b, v13
	v_mul_f32_e32 v21, 0xbfb8aa3b, v7
	v_mul_f32_e32 v22, 0xbfb8aa3b, v15
	v_mul_f32_e32 v23, 0xbfb8aa3b, v1
	v_mul_f32_e32 v24, 0xbfb8aa3b, v9
	v_exp_f32_e32 v25, v25
	v_exp_f32_e32 v16, v16
	v_exp_f32_e32 v17, v17
	v_exp_f32_e32 v20, v20
	v_exp_f32_e32 v21, v21
	v_exp_f32_e32 v22, v22
	v_exp_f32_e32 v23, v23
	v_exp_f32_e32 v24, v24
	v_add_f32_e32 v25, 1.0, v25
	v_add_f32_e32 v16, 1.0, v16
	v_add_f32_e32 v17, 1.0, v17
	v_add_f32_e32 v20, 1.0, v20
	v_add_f32_e32 v21, 1.0, v21
	v_add_f32_e32 v22, 1.0, v22
	v_add_f32_e32 v23, 1.0, v23
	v_add_f32_e32 v24, 1.0, v24
	v_rcp_f32_e32 v25, v25
	v_rcp_f32_e32 v16, v16
	v_rcp_f32_e32 v17, v17
	v_rcp_f32_e32 v20, v20
	v_rcp_f32_e32 v21, v21
	v_rcp_f32_e32 v22, v22
	v_rcp_f32_e32 v23, v23
	v_rcp_f32_e32 v24, v24
	v_mul_f32_e32 v3, v3, v25
	v_mul_f32_e32 v16, v19, v16
	v_mul_f32_e32 v5, v5, v17
	v_mul_f32_e32 v13, v13, v20
	v_mul_f32_e32 v7, v7, v21
	v_mul_f32_e32 v15, v15, v22
	v_mul_f32_e32 v1, v1, v23
	v_mul_f32_e32 v9, v9, v24
	v_mul_f32_e32 v3, v2, v3
	s_andn2_b64 vcc, exec, s[14:15]
	s_mov_b64 s[14:15], -1
	v_mul_f32_e32 v16, v18, v16
	v_mul_f32_e32 v4, v4, v5
	v_mul_f32_e32 v5, v12, v13
	v_mul_f32_e32 v6, v6, v7
	v_mul_f32_e32 v7, v14, v15
	v_mul_f32_e32 v12, v0, v1
	v_mul_f32_e32 v8, v8, v9
	v_cvt_pk_bf16_f32 v0, v16, v4
	v_cvt_pk_bf16_f32 v1, v5, v6
	v_cvt_pk_bf16_f32 v2, v7, v12
	v_cvt_pk_bf16_f32 v3, v8, v3
	global_store_dwordx4 v[10:11], v[0:3], off
	s_cbranch_vccnz .LBB0_1705
	s_andn2_b64 vcc, exec, s[0:1]
	s_cbranch_vccnz .LBB0_1704
	s_barrier
	s_branch .LBB0_1704

.LBB0_2023:
	v_lshl_add_u32 v144, s34, 8, v146
	v_ashrrev_i32_e32 v145, 31, v144
	v_lshlrev_b64 v[154:155], 6, v[144:145]
	v_lshl_add_u64 v[166:167], s[16:17], 0, v[154:155]
	global_load_dwordx4 v[154:157], v[166:167], off
	global_load_dwordx4 v[158:161], v[166:167], off offset:16
	global_load_dwordx4 v[162:165], v[166:167], off offset:32
	s_nop 0
	global_load_dwordx4 v[166:169], v[166:167], off offset:48
	v_mov_b32_e32 v174, v122
	v_mov_b32_e32 v175, v114
	v_mov_b32_e32 v114, v123
	v_mov_b32_e32 v172, v124
	v_mov_b32_e32 v173, v116
	v_mov_b32_e32 v116, v125
	v_mov_b32_e32 v124, v126
	v_mov_b32_e32 v125, v118
	v_mov_b32_e32 v118, v127
	v_mov_b32_e32 v127, v112
	v_mov_b32_e32 v112, v121
	v_mov_b32_e32 v126, v120
	v_lshl_or_b32 v170, s79, 7, v148
	v_mov_b64_e32 v[120:121], s[18:19]
	v_ashrrev_i32_e32 v171, 31, v170
	s_waitcnt vmcnt(0)
	v_mov_b32_e32 v122, v155
	v_mov_b32_e32 v123, v156
	v_mov_b32_e32 v155, v157
	v_mov_b32_e32 v156, v159
	v_mov_b32_e32 v157, v160
	v_mov_b32_e32 v159, v161
	v_pk_add_f32 v[122:123], v[122:123], v[154:155]
	v_pk_add_f32 v[154:155], v[156:157], v[158:159]
	v_pk_add_f32 v[122:123], v[122:123], v[122:123] op_sel:[0,1] op_sel_hi:[1,0]
	v_pk_add_f32 v[154:155], v[154:155], v[154:155] op_sel:[0,1] op_sel_hi:[1,0]
	v_add_f32_e32 v160, v162, v163
	v_add_f32_e32 v162, v164, v165
	v_mov_b32_e32 v161, v168
	v_mov_b32_e32 v163, v169
	v_mov_b32_e32 v123, v166
	v_mov_b32_e32 v155, v167
	v_pk_add_f32 v[156:157], v[160:161], v[162:163]
	v_pk_add_f32 v[122:123], v[122:123], v[154:155]
	v_mad_i64_i32 v[154:155], s[36:37], v144, s78, v[120:121]
	v_pk_add_f32 v[122:123], v[122:123], v[156:157]
	s_nop 0
	v_add_f32_e32 v122, v122, v123
	v_or_b32_e32 v252, 16, v144
	v_ashrrev_i32_e32 v253, 31, v252
	v_lshlrev_b64 v[252:253], 6, v[252:253]
	v_lshl_add_u64 v[254:255], s[16:17], 0, v[252:253]
	global_load_dwordx4 v[236:239], v[254:255], off
	global_load_dwordx4 v[240:243], v[254:255], off offset:16
	global_load_dwordx4 v[244:247], v[254:255], off offset:32
	global_load_dwordx4 v[248:251], v[254:255], off offset:48
	v_fmamk_f32 v122, v122, 0x3a800000, v152
	v_mul_f32_e32 v123, 0x4b800000, v122
	v_cmp_gt_f32_e32 vcc, s73, v122
	s_nop 1
	v_cndmask_b32_e32 v122, v122, v123, vcc
	v_rsq_f32_e32 v145, v122
	v_lshlrev_b64 v[122:123], 1, v[170:171]
	v_lshl_add_u64 v[154:155], v[154:155], 0, v[122:123]
	v_mul_f32_e32 v153, 0x45800000, v145
	v_cndmask_b32_e32 v156, v145, v153, vcc
	v_pk_mul_f32 v[158:159], v[172:173], v[156:157] op_sel_hi:[1,0]
	v_pk_mul_f32 v[116:117], v[116:117], v[156:157] op_sel_hi:[1,0]
	v_pk_mul_f32 v[124:125], v[124:125], v[156:157] op_sel_hi:[1,0]
	v_pk_mul_f32 v[118:119], v[118:119], v[156:157] op_sel_hi:[1,0]
	v_pk_mul_f32 v[112:113], v[112:113], v[156:157] op_sel_hi:[1,0]
	v_pk_mul_f32 v[114:115], v[114:115], v[156:157] op_sel_hi:[1,0]
	v_mul_f32_e32 v145, 0xbfb8aa3b, v159
	v_pk_mul_f32 v[126:127], v[126:127], v[156:157] op_sel_hi:[1,0]
	v_pk_mul_f32 v[160:161], v[174:175], v[156:157] op_sel_hi:[1,0]
	v_mul_f32_e32 v153, 0xbfb8aa3b, v117
	v_mul_f32_e32 v156, 0xbfb8aa3b, v125
	v_mul_f32_e32 v157, 0xbfb8aa3b, v119
	v_mul_f32_e32 v163, 0xbfb8aa3b, v113
	v_mul_f32_e32 v165, 0xbfb8aa3b, v115
	v_exp_f32_e32 v145, v145
	v_mul_f32_e32 v162, 0xbfb8aa3b, v127
	v_mul_f32_e32 v164, 0xbfb8aa3b, v161
	v_exp_f32_e32 v153, v153
	v_exp_f32_e32 v156, v156
	v_exp_f32_e32 v157, v157
	v_exp_f32_e32 v163, v163
	v_exp_f32_e32 v165, v165
	v_exp_f32_e32 v162, v162
	v_exp_f32_e32 v164, v164
	v_add_f32_e32 v145, 1.0, v145
	v_add_f32_e32 v153, 1.0, v153
	v_add_f32_e32 v156, 1.0, v156
	v_add_f32_e32 v157, 1.0, v157
	v_add_f32_e32 v163, 1.0, v163
	v_add_f32_e32 v165, 1.0, v165
	v_rcp_f32_e32 v145, v145
	v_add_f32_e32 v162, 1.0, v162
	v_add_f32_e32 v164, 1.0, v164
	v_rcp_f32_e32 v153, v153
	v_rcp_f32_e32 v156, v156
	v_rcp_f32_e32 v157, v157
	v_rcp_f32_e32 v163, v163
	v_rcp_f32_e32 v165, v165
	v_rcp_f32_e32 v162, v162
	v_rcp_f32_e32 v164, v164
	v_mul_f32_e32 v145, v159, v145
	v_mul_f32_e32 v117, v117, v153
	v_mul_f32_e32 v125, v125, v156
	v_mul_f32_e32 v119, v119, v157
	v_mul_f32_e32 v113, v113, v163
	v_mul_f32_e32 v115, v115, v165
	v_mul_f32_e32 v145, v158, v145
	v_or_b32_e32 v158, 16, v144
	v_mul_f32_e32 v127, v127, v162
	v_mul_f32_e32 v153, v161, v164
	v_mul_f32_e32 v116, v116, v117
	v_mul_f32_e32 v117, v124, v125
	v_mul_f32_e32 v118, v118, v119
	v_mul_f32_e32 v124, v112, v113
	v_mul_f32_e32 v115, v114, v115
	v_cvt_pk_bf16_f32 v112, v145, v116
	v_cvt_pk_bf16_f32 v113, v117, v118
	v_ashrrev_i32_e32 v159, 31, v158
	v_mul_f32_e32 v119, v126, v127
	v_mul_f32_e32 v125, v160, v153
	v_cvt_pk_bf16_f32 v114, v119, v124
	v_cvt_pk_bf16_f32 v115, v125, v115
	global_store_dwordx4 v[154:155], v[112:115], off
	v_mov_b32_e32 v160, v108
	v_mov_b32_e32 v161, v100
	v_mov_b32_e32 v100, v109
	v_mov_b32_e32 v108, v110
	v_mov_b32_e32 v109, v102
	v_mov_b32_e32 v102, v111
	v_mov_b32_e32 v110, v104
	v_mov_b32_e32 v111, v96
	v_mov_b32_e32 v96, v105
	v_mov_b32_e32 v104, v106
	v_mov_b32_e32 v105, v98
	v_mov_b32_e32 v98, v107
	s_waitcnt vmcnt(1)
	v_pk_add_f32 v[236:237], v[236:237], v[238:239]
	v_pk_add_f32 v[240:241], v[240:241], v[242:243]
	v_pk_add_f32 v[244:245], v[244:245], v[246:247]
	v_pk_add_f32 v[248:249], v[248:249], v[250:251]
	v_pk_add_f32 v[236:237], v[236:237], v[240:241]
	v_pk_add_f32 v[244:245], v[244:245], v[248:249]
	s_nop 0
	v_pk_add_f32 v[236:237], v[236:237], v[244:245]
	s_nop 0
	v_add_f32_e32 v106, v236, v237
	v_or_b32_e32 v252, 32, v144
	v_ashrrev_i32_e32 v253, 31, v252
	v_lshlrev_b64 v[252:253], 6, v[252:253]
	v_lshl_add_u64 v[254:255], s[16:17], 0, v[252:253]
	global_load_dwordx4 v[236:239], v[254:255], off
	global_load_dwordx4 v[240:243], v[254:255], off offset:16
	global_load_dwordx4 v[244:247], v[254:255], off offset:32
	global_load_dwordx4 v[248:251], v[254:255], off offset:48
	v_fmamk_f32 v106, v106, 0x3a800000, v152
	v_mul_f32_e32 v107, 0x4b800000, v106
	v_cmp_gt_f32_e32 vcc, s73, v106
	s_nop 1
	v_cndmask_b32_e32 v106, v106, v107, vcc
	v_rsq_f32_e32 v112, v106
	v_mad_i64_i32 v[106:107], s[36:37], v158, s78, v[120:121]
	v_lshl_add_u64 v[106:107], v[106:107], 0, v[122:123]
	v_mul_f32_e32 v113, 0x45800000, v112
	v_cndmask_b32_e32 v112, v112, v113, vcc
	v_pk_mul_f32 v[114:115], v[160:161], v[112:113] op_sel_hi:[1,0]
	v_pk_mul_f32 v[100:101], v[100:101], v[112:113] op_sel_hi:[1,0]
	v_pk_mul_f32 v[108:109], v[108:109], v[112:113] op_sel_hi:[1,0]
	v_pk_mul_f32 v[102:103], v[102:103], v[112:113] op_sel_hi:[1,0]
	v_pk_mul_f32 v[110:111], v[110:111], v[112:113] op_sel_hi:[1,0]
	v_pk_mul_f32 v[96:97], v[96:97], v[112:113] op_sel_hi:[1,0]
	v_pk_mul_f32 v[104:105], v[104:105], v[112:113] op_sel_hi:[1,0]
	v_pk_mul_f32 v[98:99], v[98:99], v[112:113] op_sel_hi:[1,0]
	v_mul_f32_e32 v112, 0xbfb8aa3b, v115
	v_mul_f32_e32 v113, 0xbfb8aa3b, v101
	v_mul_f32_e32 v116, 0xbfb8aa3b, v109
	v_mul_f32_e32 v119, 0xbfb8aa3b, v97
	v_exp_f32_e32 v112, v112
	v_mul_f32_e32 v117, 0xbfb8aa3b, v103
	v_mul_f32_e32 v125, 0xbfb8aa3b, v99
	v_exp_f32_e32 v113, v113
	v_exp_f32_e32 v116, v116
	v_exp_f32_e32 v119, v119
	v_mul_f32_e32 v118, 0xbfb8aa3b, v111
	v_mul_f32_e32 v124, 0xbfb8aa3b, v105
	v_exp_f32_e32 v117, v117
	v_exp_f32_e32 v125, v125
	v_exp_f32_e32 v118, v118
	v_exp_f32_e32 v124, v124
	v_add_f32_e32 v112, 1.0, v112
	v_add_f32_e32 v113, 1.0, v113
	v_add_f32_e32 v116, 1.0, v116
	v_add_f32_e32 v119, 1.0, v119
	v_rcp_f32_e32 v112, v112
	v_add_f32_e32 v117, 1.0, v117
	v_add_f32_e32 v125, 1.0, v125
	v_rcp_f32_e32 v113, v113
	v_rcp_f32_e32 v116, v116
	v_rcp_f32_e32 v119, v119
	v_add_f32_e32 v118, 1.0, v118
	v_add_f32_e32 v124, 1.0, v124
	v_rcp_f32_e32 v117, v117
	v_rcp_f32_e32 v125, v125
	v_rcp_f32_e32 v118, v118
	v_rcp_f32_e32 v124, v124
	v_mul_f32_e32 v112, v115, v112
	v_mul_f32_e32 v101, v101, v113
	v_mul_f32_e32 v109, v109, v116
	v_mul_f32_e32 v97, v97, v119
	v_mul_f32_e32 v112, v114, v112
	v_mul_f32_e32 v103, v103, v117
	v_mul_f32_e32 v99, v99, v125
	v_mul_f32_e32 v100, v100, v101
	v_mul_f32_e32 v101, v108, v109
	v_mul_f32_e32 v108, v96, v97
	v_cvt_pk_bf16_f32 v96, v112, v100
	v_or_b32_e32 v112, 32, v144
	v_mul_f32_e32 v111, v111, v118
	v_mul_f32_e32 v105, v105, v124
	v_mul_f32_e32 v102, v102, v103
	v_mul_f32_e32 v99, v98, v99
	v_cvt_pk_bf16_f32 v97, v101, v102
	v_ashrrev_i32_e32 v113, 31, v112
	v_mul_f32_e32 v103, v110, v111
	v_mul_f32_e32 v104, v104, v105
	v_cvt_pk_bf16_f32 v98, v103, v108
	v_cvt_pk_bf16_f32 v99, v104, v99
	global_store_dwordx4 v[106:107], v[96:99], off
	v_mov_b32_e32 v114, v92
	v_mov_b32_e32 v115, v84
	v_mov_b32_e32 v84, v93
	v_mov_b32_e32 v92, v94
	v_mov_b32_e32 v93, v86
	v_mov_b32_e32 v86, v95
	v_mov_b32_e32 v94, v88
	v_mov_b32_e32 v95, v80
	v_mov_b32_e32 v80, v89
	v_mov_b32_e32 v88, v90
	v_mov_b32_e32 v89, v82
	v_mov_b32_e32 v82, v91
	s_waitcnt vmcnt(1)
	v_pk_add_f32 v[236:237], v[236:237], v[238:239]
	v_pk_add_f32 v[240:241], v[240:241], v[242:243]
	v_pk_add_f32 v[244:245], v[244:245], v[246:247]
	v_pk_add_f32 v[248:249], v[248:249], v[250:251]
	v_pk_add_f32 v[236:237], v[236:237], v[240:241]
	v_pk_add_f32 v[244:245], v[244:245], v[248:249]
	s_nop 0
	v_pk_add_f32 v[236:237], v[236:237], v[244:245]
	s_nop 0
	v_add_f32_e32 v90, v236, v237
	v_or_b32_e32 v252, 48, v144
	v_ashrrev_i32_e32 v253, 31, v252
	v_lshlrev_b64 v[252:253], 6, v[252:253]
	v_lshl_add_u64 v[254:255], s[16:17], 0, v[252:253]
	global_load_dwordx4 v[236:239], v[254:255], off
	global_load_dwordx4 v[240:243], v[254:255], off offset:16
	global_load_dwordx4 v[244:247], v[254:255], off offset:32
	global_load_dwordx4 v[248:251], v[254:255], off offset:48
	v_fmamk_f32 v90, v90, 0x3a800000, v152
	v_mul_f32_e32 v91, 0x4b800000, v90
	v_cmp_gt_f32_e32 vcc, s73, v90
	s_nop 1
	v_cndmask_b32_e32 v90, v90, v91, vcc
	v_rsq_f32_e32 v96, v90
	v_mad_i64_i32 v[90:91], s[36:37], v112, s78, v[120:121]
	v_lshl_add_u64 v[90:91], v[90:91], 0, v[122:123]
	v_mul_f32_e32 v97, 0x45800000, v96
	v_cndmask_b32_e32 v96, v96, v97, vcc
	v_pk_mul_f32 v[98:99], v[114:115], v[96:97] op_sel_hi:[1,0]
	v_pk_mul_f32 v[84:85], v[84:85], v[96:97] op_sel_hi:[1,0]
	v_pk_mul_f32 v[92:93], v[92:93], v[96:97] op_sel_hi:[1,0]
	v_pk_mul_f32 v[86:87], v[86:87], v[96:97] op_sel_hi:[1,0]
	v_pk_mul_f32 v[94:95], v[94:95], v[96:97] op_sel_hi:[1,0]
	v_pk_mul_f32 v[80:81], v[80:81], v[96:97] op_sel_hi:[1,0]
	v_pk_mul_f32 v[88:89], v[88:89], v[96:97] op_sel_hi:[1,0]
	v_pk_mul_f32 v[82:83], v[82:83], v[96:97] op_sel_hi:[1,0]
	v_mul_f32_e32 v96, 0xbfb8aa3b, v99
	v_mul_f32_e32 v97, 0xbfb8aa3b, v85
	v_mul_f32_e32 v100, 0xbfb8aa3b, v93
	v_mul_f32_e32 v103, 0xbfb8aa3b, v81
	v_exp_f32_e32 v96, v96
	v_mul_f32_e32 v101, 0xbfb8aa3b, v87
	v_mul_f32_e32 v105, 0xbfb8aa3b, v83
	v_exp_f32_e32 v97, v97
	v_exp_f32_e32 v100, v100
	v_exp_f32_e32 v103, v103
	v_mul_f32_e32 v102, 0xbfb8aa3b, v95
	v_mul_f32_e32 v104, 0xbfb8aa3b, v89
	v_exp_f32_e32 v101, v101
	v_exp_f32_e32 v105, v105
	v_exp_f32_e32 v102, v102
	v_exp_f32_e32 v104, v104
	v_add_f32_e32 v96, 1.0, v96
	v_add_f32_e32 v97, 1.0, v97
	v_add_f32_e32 v100, 1.0, v100
	v_add_f32_e32 v103, 1.0, v103
	v_rcp_f32_e32 v96, v96
	v_add_f32_e32 v101, 1.0, v101
	v_add_f32_e32 v105, 1.0, v105
	v_rcp_f32_e32 v97, v97
	v_rcp_f32_e32 v100, v100
	v_rcp_f32_e32 v103, v103
	v_add_f32_e32 v102, 1.0, v102
	v_add_f32_e32 v104, 1.0, v104
	v_rcp_f32_e32 v101, v101
	v_rcp_f32_e32 v105, v105
	v_rcp_f32_e32 v102, v102
	v_rcp_f32_e32 v104, v104
	v_mul_f32_e32 v96, v99, v96
	v_mul_f32_e32 v85, v85, v97
	v_mul_f32_e32 v93, v93, v100
	v_mul_f32_e32 v81, v81, v103
	v_mul_f32_e32 v96, v98, v96
	v_mul_f32_e32 v87, v87, v101
	v_mul_f32_e32 v83, v83, v105
	v_mul_f32_e32 v84, v84, v85
	v_mul_f32_e32 v85, v92, v93
	v_mul_f32_e32 v92, v80, v81
	v_cvt_pk_bf16_f32 v80, v96, v84
	v_or_b32_e32 v96, 48, v144
	v_mul_f32_e32 v95, v95, v102
	v_mul_f32_e32 v89, v89, v104
	v_mul_f32_e32 v86, v86, v87
	v_mul_f32_e32 v83, v82, v83
	v_cvt_pk_bf16_f32 v81, v85, v86
	v_ashrrev_i32_e32 v97, 31, v96
	v_mul_f32_e32 v87, v94, v95
	v_mul_f32_e32 v88, v88, v89
	v_cvt_pk_bf16_f32 v82, v87, v92
	v_cvt_pk_bf16_f32 v83, v88, v83
	global_store_dwordx4 v[90:91], v[80:83], off
	v_mov_b32_e32 v98, v76
	v_mov_b32_e32 v99, v68
	v_mov_b32_e32 v68, v77
	v_mov_b32_e32 v76, v78
	v_mov_b32_e32 v77, v70
	v_mov_b32_e32 v70, v79
	v_mov_b32_e32 v78, v72
	v_mov_b32_e32 v79, v64
	v_mov_b32_e32 v64, v73
	v_mov_b32_e32 v72, v74
	v_mov_b32_e32 v73, v66
	v_mov_b32_e32 v66, v75
	s_waitcnt vmcnt(1)
	v_pk_add_f32 v[236:237], v[236:237], v[238:239]
	v_pk_add_f32 v[240:241], v[240:241], v[242:243]
	v_pk_add_f32 v[244:245], v[244:245], v[246:247]
	v_pk_add_f32 v[248:249], v[248:249], v[250:251]
	v_pk_add_f32 v[236:237], v[236:237], v[240:241]
	v_pk_add_f32 v[244:245], v[244:245], v[248:249]
	s_nop 0
	v_pk_add_f32 v[236:237], v[236:237], v[244:245]
	s_nop 0
	v_add_f32_e32 v74, v236, v237
	v_add_u32_e32 v252, 0x80, v144
	v_ashrrev_i32_e32 v253, 31, v252
	v_lshlrev_b64 v[252:253], 6, v[252:253]
	v_lshl_add_u64 v[254:255], s[16:17], 0, v[252:253]
	global_load_dwordx4 v[236:239], v[254:255], off
	global_load_dwordx4 v[240:243], v[254:255], off offset:16
	global_load_dwordx4 v[244:247], v[254:255], off offset:32
	global_load_dwordx4 v[248:251], v[254:255], off offset:48
	v_fmamk_f32 v74, v74, 0x3a800000, v152
	v_mul_f32_e32 v75, 0x4b800000, v74
	v_cmp_gt_f32_e32 vcc, s73, v74
	s_nop 1
	v_cndmask_b32_e32 v74, v74, v75, vcc
	v_rsq_f32_e32 v80, v74
	v_mad_i64_i32 v[74:75], s[36:37], v96, s78, v[120:121]
	v_lshl_add_u64 v[74:75], v[74:75], 0, v[122:123]
	v_mul_f32_e32 v81, 0x45800000, v80
	v_cndmask_b32_e32 v80, v80, v81, vcc
	v_pk_mul_f32 v[82:83], v[98:99], v[80:81] op_sel_hi:[1,0]
	v_pk_mul_f32 v[68:69], v[68:69], v[80:81] op_sel_hi:[1,0]
	v_pk_mul_f32 v[76:77], v[76:77], v[80:81] op_sel_hi:[1,0]
	v_pk_mul_f32 v[70:71], v[70:71], v[80:81] op_sel_hi:[1,0]
	v_pk_mul_f32 v[78:79], v[78:79], v[80:81] op_sel_hi:[1,0]
	v_pk_mul_f32 v[64:65], v[64:65], v[80:81] op_sel_hi:[1,0]
	v_pk_mul_f32 v[72:73], v[72:73], v[80:81] op_sel_hi:[1,0]
	v_pk_mul_f32 v[66:67], v[66:67], v[80:81] op_sel_hi:[1,0]
	v_mul_f32_e32 v80, 0xbfb8aa3b, v83
	v_mul_f32_e32 v81, 0xbfb8aa3b, v69
	v_mul_f32_e32 v84, 0xbfb8aa3b, v77
	v_mul_f32_e32 v87, 0xbfb8aa3b, v65
	v_exp_f32_e32 v80, v80
	v_mul_f32_e32 v85, 0xbfb8aa3b, v71
	v_mul_f32_e32 v89, 0xbfb8aa3b, v67
	v_exp_f32_e32 v81, v81
	v_exp_f32_e32 v84, v84
	v_exp_f32_e32 v87, v87
	v_mul_f32_e32 v86, 0xbfb8aa3b, v79
	v_mul_f32_e32 v88, 0xbfb8aa3b, v73
	v_exp_f32_e32 v85, v85
	v_exp_f32_e32 v89, v89
	v_exp_f32_e32 v86, v86
	v_exp_f32_e32 v88, v88
	v_add_f32_e32 v80, 1.0, v80
	v_add_f32_e32 v81, 1.0, v81
	v_add_f32_e32 v84, 1.0, v84
	v_add_f32_e32 v87, 1.0, v87
	v_rcp_f32_e32 v80, v80
	v_add_f32_e32 v85, 1.0, v85
	v_add_f32_e32 v89, 1.0, v89
	v_rcp_f32_e32 v81, v81
	v_rcp_f32_e32 v84, v84
	v_rcp_f32_e32 v87, v87
	v_add_f32_e32 v86, 1.0, v86
	v_add_f32_e32 v88, 1.0, v88
	v_rcp_f32_e32 v85, v85
	v_rcp_f32_e32 v89, v89
	v_rcp_f32_e32 v86, v86
	v_rcp_f32_e32 v88, v88
	v_mul_f32_e32 v80, v83, v80
	v_mul_f32_e32 v69, v69, v81
	v_mul_f32_e32 v77, v77, v84
	v_mul_f32_e32 v65, v65, v87
	v_mul_f32_e32 v80, v82, v80
	v_mul_f32_e32 v71, v71, v85
	v_mul_f32_e32 v67, v67, v89
	v_mul_f32_e32 v68, v68, v69
	v_mul_f32_e32 v69, v76, v77
	v_mul_f32_e32 v76, v64, v65
	v_cvt_pk_bf16_f32 v64, v80, v68
	v_add_u32_e32 v80, 0x80, v144
	v_mul_f32_e32 v79, v79, v86
	v_mul_f32_e32 v73, v73, v88
	v_mul_f32_e32 v70, v70, v71
	v_mul_f32_e32 v67, v66, v67
	v_cvt_pk_bf16_f32 v65, v69, v70
	v_ashrrev_i32_e32 v81, 31, v80
	v_mul_f32_e32 v71, v78, v79
	v_mul_f32_e32 v72, v72, v73
	v_cvt_pk_bf16_f32 v66, v71, v76
	v_cvt_pk_bf16_f32 v67, v72, v67
	global_store_dwordx4 v[74:75], v[64:67], off
	v_mov_b32_e32 v82, v60
	v_mov_b32_e32 v83, v52
	v_mov_b32_e32 v52, v61
	v_mov_b32_e32 v60, v62
	v_mov_b32_e32 v61, v54
	v_mov_b32_e32 v54, v63
	v_mov_b32_e32 v62, v56
	v_mov_b32_e32 v63, v48
	v_mov_b32_e32 v48, v57
	v_mov_b32_e32 v56, v58
	v_mov_b32_e32 v57, v50
	v_mov_b32_e32 v50, v59
	s_waitcnt vmcnt(1)
	v_pk_add_f32 v[236:237], v[236:237], v[238:239]
	v_pk_add_f32 v[240:241], v[240:241], v[242:243]
	v_pk_add_f32 v[244:245], v[244:245], v[246:247]
	v_pk_add_f32 v[248:249], v[248:249], v[250:251]
	v_pk_add_f32 v[236:237], v[236:237], v[240:241]
	v_pk_add_f32 v[244:245], v[244:245], v[248:249]
	s_nop 0
	v_pk_add_f32 v[236:237], v[236:237], v[244:245]
	s_nop 0
	v_add_f32_e32 v58, v236, v237
	v_add_u32_e32 v252, 0x90, v144
	v_ashrrev_i32_e32 v253, 31, v252
	v_lshlrev_b64 v[252:253], 6, v[252:253]
	v_lshl_add_u64 v[254:255], s[16:17], 0, v[252:253]
	global_load_dwordx4 v[236:239], v[254:255], off
	global_load_dwordx4 v[240:243], v[254:255], off offset:16
	global_load_dwordx4 v[244:247], v[254:255], off offset:32
	global_load_dwordx4 v[248:251], v[254:255], off offset:48
	v_fmamk_f32 v58, v58, 0x3a800000, v152
	v_mul_f32_e32 v59, 0x4b800000, v58
	v_cmp_gt_f32_e32 vcc, s73, v58
	s_nop 1
	v_cndmask_b32_e32 v58, v58, v59, vcc
	v_rsq_f32_e32 v64, v58
	v_mad_i64_i32 v[58:59], s[36:37], v80, s78, v[120:121]
	v_lshl_add_u64 v[58:59], v[58:59], 0, v[122:123]
	v_mul_f32_e32 v65, 0x45800000, v64
	v_cndmask_b32_e32 v64, v64, v65, vcc
	v_pk_mul_f32 v[66:67], v[82:83], v[64:65] op_sel_hi:[1,0]
	v_pk_mul_f32 v[52:53], v[52:53], v[64:65] op_sel_hi:[1,0]
	v_pk_mul_f32 v[60:61], v[60:61], v[64:65] op_sel_hi:[1,0]
	v_pk_mul_f32 v[54:55], v[54:55], v[64:65] op_sel_hi:[1,0]
	v_pk_mul_f32 v[62:63], v[62:63], v[64:65] op_sel_hi:[1,0]
	v_pk_mul_f32 v[48:49], v[48:49], v[64:65] op_sel_hi:[1,0]
	v_pk_mul_f32 v[56:57], v[56:57], v[64:65] op_sel_hi:[1,0]
	v_pk_mul_f32 v[50:51], v[50:51], v[64:65] op_sel_hi:[1,0]
	v_mul_f32_e32 v64, 0xbfb8aa3b, v67
	v_mul_f32_e32 v65, 0xbfb8aa3b, v53
	v_mul_f32_e32 v68, 0xbfb8aa3b, v61
	v_mul_f32_e32 v71, 0xbfb8aa3b, v49
	v_exp_f32_e32 v64, v64
	v_mul_f32_e32 v69, 0xbfb8aa3b, v55
	v_mul_f32_e32 v73, 0xbfb8aa3b, v51
	v_exp_f32_e32 v65, v65
	v_exp_f32_e32 v68, v68
	v_exp_f32_e32 v71, v71
	v_mul_f32_e32 v70, 0xbfb8aa3b, v63
	v_mul_f32_e32 v72, 0xbfb8aa3b, v57
	v_exp_f32_e32 v69, v69
	v_exp_f32_e32 v73, v73
	v_exp_f32_e32 v70, v70
	v_exp_f32_e32 v72, v72
	v_add_f32_e32 v64, 1.0, v64
	v_add_f32_e32 v65, 1.0, v65
	v_add_f32_e32 v68, 1.0, v68
	v_add_f32_e32 v71, 1.0, v71
	v_rcp_f32_e32 v64, v64
	v_add_f32_e32 v69, 1.0, v69
	v_add_f32_e32 v73, 1.0, v73
	v_rcp_f32_e32 v65, v65
	v_rcp_f32_e32 v68, v68
	v_rcp_f32_e32 v71, v71
	v_add_f32_e32 v70, 1.0, v70
	v_add_f32_e32 v72, 1.0, v72
	v_rcp_f32_e32 v69, v69
	v_rcp_f32_e32 v73, v73
	v_rcp_f32_e32 v70, v70
	v_rcp_f32_e32 v72, v72
	v_mul_f32_e32 v64, v67, v64
	v_mul_f32_e32 v53, v53, v65
	v_mul_f32_e32 v61, v61, v68
	v_mul_f32_e32 v49, v49, v71
	v_mul_f32_e32 v64, v66, v64
	v_mul_f32_e32 v55, v55, v69
	v_mul_f32_e32 v51, v51, v73
	v_mul_f32_e32 v52, v52, v53
	v_mul_f32_e32 v53, v60, v61
	v_mul_f32_e32 v60, v48, v49
	v_cvt_pk_bf16_f32 v48, v64, v52
	v_add_u32_e32 v64, 0x90, v144
	v_mul_f32_e32 v63, v63, v70
	v_mul_f32_e32 v57, v57, v72
	v_mul_f32_e32 v54, v54, v55
	v_mul_f32_e32 v51, v50, v51
	v_cvt_pk_bf16_f32 v49, v53, v54
	v_ashrrev_i32_e32 v65, 31, v64
	v_mul_f32_e32 v55, v62, v63
	v_mul_f32_e32 v56, v56, v57
	v_cvt_pk_bf16_f32 v50, v55, v60
	v_cvt_pk_bf16_f32 v51, v56, v51
	global_store_dwordx4 v[58:59], v[48:51], off
	v_mov_b32_e32 v66, v44
	v_mov_b32_e32 v67, v36
	v_mov_b32_e32 v36, v45
	v_mov_b32_e32 v44, v46
	v_mov_b32_e32 v45, v38
	v_mov_b32_e32 v38, v47
	v_mov_b32_e32 v46, v40
	v_mov_b32_e32 v47, v32
	v_mov_b32_e32 v32, v41
	v_mov_b32_e32 v40, v42
	v_mov_b32_e32 v41, v34
	v_mov_b32_e32 v34, v43
	s_waitcnt vmcnt(1)
	v_pk_add_f32 v[236:237], v[236:237], v[238:239]
	v_pk_add_f32 v[240:241], v[240:241], v[242:243]
	v_pk_add_f32 v[244:245], v[244:245], v[246:247]
	v_pk_add_f32 v[248:249], v[248:249], v[250:251]
	v_pk_add_f32 v[236:237], v[236:237], v[240:241]
	v_pk_add_f32 v[244:245], v[244:245], v[248:249]
	s_nop 0
	v_pk_add_f32 v[236:237], v[236:237], v[244:245]
	s_nop 0
	v_add_f32_e32 v42, v236, v237
	v_add_u32_e32 v252, 0xa0, v144
	v_ashrrev_i32_e32 v253, 31, v252
	v_lshlrev_b64 v[252:253], 6, v[252:253]
	v_lshl_add_u64 v[254:255], s[16:17], 0, v[252:253]
	global_load_dwordx4 v[236:239], v[254:255], off
	global_load_dwordx4 v[240:243], v[254:255], off offset:16
	global_load_dwordx4 v[244:247], v[254:255], off offset:32
	global_load_dwordx4 v[248:251], v[254:255], off offset:48
	v_fmamk_f32 v42, v42, 0x3a800000, v152
	v_mul_f32_e32 v43, 0x4b800000, v42
	v_cmp_gt_f32_e32 vcc, s73, v42
	s_nop 1
	v_cndmask_b32_e32 v42, v42, v43, vcc
	v_rsq_f32_e32 v48, v42
	v_mad_i64_i32 v[42:43], s[36:37], v64, s78, v[120:121]
	v_lshl_add_u64 v[42:43], v[42:43], 0, v[122:123]
	v_mul_f32_e32 v49, 0x45800000, v48
	v_cndmask_b32_e32 v48, v48, v49, vcc
	v_pk_mul_f32 v[50:51], v[66:67], v[48:49] op_sel_hi:[1,0]
	v_pk_mul_f32 v[36:37], v[36:37], v[48:49] op_sel_hi:[1,0]
	v_pk_mul_f32 v[44:45], v[44:45], v[48:49] op_sel_hi:[1,0]
	v_pk_mul_f32 v[38:39], v[38:39], v[48:49] op_sel_hi:[1,0]
	v_pk_mul_f32 v[46:47], v[46:47], v[48:49] op_sel_hi:[1,0]
	v_pk_mul_f32 v[32:33], v[32:33], v[48:49] op_sel_hi:[1,0]
	v_pk_mul_f32 v[40:41], v[40:41], v[48:49] op_sel_hi:[1,0]
	v_pk_mul_f32 v[34:35], v[34:35], v[48:49] op_sel_hi:[1,0]
	v_mul_f32_e32 v48, 0xbfb8aa3b, v51
	v_mul_f32_e32 v49, 0xbfb8aa3b, v37
	v_mul_f32_e32 v52, 0xbfb8aa3b, v45
	v_mul_f32_e32 v55, 0xbfb8aa3b, v33
	v_exp_f32_e32 v48, v48
	v_mul_f32_e32 v53, 0xbfb8aa3b, v39
	v_mul_f32_e32 v57, 0xbfb8aa3b, v35
	v_exp_f32_e32 v49, v49
	v_exp_f32_e32 v52, v52
	v_exp_f32_e32 v55, v55
	v_mul_f32_e32 v54, 0xbfb8aa3b, v47
	v_mul_f32_e32 v56, 0xbfb8aa3b, v41
	v_exp_f32_e32 v53, v53
	v_exp_f32_e32 v57, v57
	v_exp_f32_e32 v54, v54
	v_exp_f32_e32 v56, v56
	v_add_f32_e32 v48, 1.0, v48
	v_add_f32_e32 v49, 1.0, v49
	v_add_f32_e32 v52, 1.0, v52
	v_add_f32_e32 v55, 1.0, v55
	v_rcp_f32_e32 v48, v48
	v_add_f32_e32 v53, 1.0, v53
	v_add_f32_e32 v57, 1.0, v57
	v_rcp_f32_e32 v49, v49
	v_rcp_f32_e32 v52, v52
	v_rcp_f32_e32 v55, v55
	v_add_f32_e32 v54, 1.0, v54
	v_add_f32_e32 v56, 1.0, v56
	v_rcp_f32_e32 v53, v53
	v_rcp_f32_e32 v57, v57
	v_rcp_f32_e32 v54, v54
	v_rcp_f32_e32 v56, v56
	v_mul_f32_e32 v48, v51, v48
	v_mul_f32_e32 v37, v37, v49
	v_mul_f32_e32 v45, v45, v52
	v_mul_f32_e32 v33, v33, v55
	v_mul_f32_e32 v48, v50, v48
	v_mul_f32_e32 v39, v39, v53
	v_mul_f32_e32 v35, v35, v57
	v_mul_f32_e32 v36, v36, v37
	v_mul_f32_e32 v37, v44, v45
	v_mul_f32_e32 v44, v32, v33
	v_cvt_pk_bf16_f32 v32, v48, v36
	v_add_u32_e32 v48, 0xa0, v144
	v_mul_f32_e32 v47, v47, v54
	v_mul_f32_e32 v41, v41, v56
	v_mul_f32_e32 v38, v38, v39
	v_mul_f32_e32 v35, v34, v35
	v_cvt_pk_bf16_f32 v33, v37, v38
	v_ashrrev_i32_e32 v49, 31, v48
	v_mul_f32_e32 v39, v46, v47
	v_mul_f32_e32 v40, v40, v41
	v_cvt_pk_bf16_f32 v34, v39, v44
	v_cvt_pk_bf16_f32 v35, v40, v35
	global_store_dwordx4 v[42:43], v[32:35], off
	v_mov_b32_e32 v50, v28
	v_mov_b32_e32 v51, v20
	v_mov_b32_e32 v20, v29
	v_mov_b32_e32 v28, v30
	v_mov_b32_e32 v29, v22
	v_mov_b32_e32 v22, v31
	v_mov_b32_e32 v30, v24
	v_mov_b32_e32 v31, v16
	v_mov_b32_e32 v16, v25
	v_mov_b32_e32 v24, v26
	v_mov_b32_e32 v25, v18
	v_mov_b32_e32 v18, v27
	s_waitcnt vmcnt(1)
	v_pk_add_f32 v[236:237], v[236:237], v[238:239]
	v_pk_add_f32 v[240:241], v[240:241], v[242:243]
	v_pk_add_f32 v[244:245], v[244:245], v[246:247]
	v_pk_add_f32 v[248:249], v[248:249], v[250:251]
	v_pk_add_f32 v[236:237], v[236:237], v[240:241]
	v_pk_add_f32 v[244:245], v[244:245], v[248:249]
	s_nop 0
	v_pk_add_f32 v[236:237], v[236:237], v[244:245]
	s_nop 0
	v_add_f32_e32 v26, v236, v237
	v_add_u32_e32 v252, 0xb0, v144
	v_ashrrev_i32_e32 v253, 31, v252
	v_lshlrev_b64 v[252:253], 6, v[252:253]
	v_lshl_add_u64 v[254:255], s[16:17], 0, v[252:253]
	global_load_dwordx4 v[236:239], v[254:255], off
	global_load_dwordx4 v[240:243], v[254:255], off offset:16
	global_load_dwordx4 v[244:247], v[254:255], off offset:32
	global_load_dwordx4 v[248:251], v[254:255], off offset:48
	v_fmamk_f32 v26, v26, 0x3a800000, v152
	v_mul_f32_e32 v27, 0x4b800000, v26
	v_cmp_gt_f32_e32 vcc, s73, v26
	s_nop 1
	v_cndmask_b32_e32 v26, v26, v27, vcc
	v_rsq_f32_e32 v32, v26
	v_mad_i64_i32 v[26:27], s[36:37], v48, s78, v[120:121]
	v_lshl_add_u64 v[26:27], v[26:27], 0, v[122:123]
	v_mul_f32_e32 v33, 0x45800000, v32
	v_cndmask_b32_e32 v32, v32, v33, vcc
	v_pk_mul_f32 v[34:35], v[50:51], v[32:33] op_sel_hi:[1,0]
	v_pk_mul_f32 v[20:21], v[20:21], v[32:33] op_sel_hi:[1,0]
	v_pk_mul_f32 v[28:29], v[28:29], v[32:33] op_sel_hi:[1,0]
	v_pk_mul_f32 v[22:23], v[22:23], v[32:33] op_sel_hi:[1,0]
	v_pk_mul_f32 v[30:31], v[30:31], v[32:33] op_sel_hi:[1,0]
	v_pk_mul_f32 v[16:17], v[16:17], v[32:33] op_sel_hi:[1,0]
	v_pk_mul_f32 v[24:25], v[24:25], v[32:33] op_sel_hi:[1,0]
	v_pk_mul_f32 v[18:19], v[18:19], v[32:33] op_sel_hi:[1,0]
	v_mul_f32_e32 v32, 0xbfb8aa3b, v35
	v_mul_f32_e32 v33, 0xbfb8aa3b, v21
	v_mul_f32_e32 v36, 0xbfb8aa3b, v29
	v_mul_f32_e32 v39, 0xbfb8aa3b, v17
	v_exp_f32_e32 v32, v32
	v_mul_f32_e32 v37, 0xbfb8aa3b, v23
	v_mul_f32_e32 v41, 0xbfb8aa3b, v19
	v_exp_f32_e32 v33, v33
	v_exp_f32_e32 v36, v36
	v_exp_f32_e32 v39, v39
	v_mul_f32_e32 v38, 0xbfb8aa3b, v31
	v_mul_f32_e32 v40, 0xbfb8aa3b, v25
	v_exp_f32_e32 v37, v37
	v_exp_f32_e32 v41, v41
	v_exp_f32_e32 v38, v38
	v_exp_f32_e32 v40, v40
	v_add_f32_e32 v32, 1.0, v32
	v_add_f32_e32 v33, 1.0, v33
	v_add_f32_e32 v36, 1.0, v36
	v_add_f32_e32 v39, 1.0, v39
	v_rcp_f32_e32 v32, v32
	v_add_f32_e32 v37, 1.0, v37
	v_add_f32_e32 v41, 1.0, v41
	v_rcp_f32_e32 v33, v33
	v_rcp_f32_e32 v36, v36
	v_rcp_f32_e32 v39, v39
	v_add_f32_e32 v38, 1.0, v38
	v_add_f32_e32 v40, 1.0, v40
	v_rcp_f32_e32 v37, v37
	v_rcp_f32_e32 v41, v41
	v_rcp_f32_e32 v38, v38
	v_rcp_f32_e32 v40, v40
	v_mul_f32_e32 v32, v35, v32
	v_mul_f32_e32 v21, v21, v33
	v_mul_f32_e32 v29, v29, v36
	v_mul_f32_e32 v17, v17, v39
	v_mul_f32_e32 v32, v34, v32
	v_mul_f32_e32 v23, v23, v37
	v_mul_f32_e32 v19, v19, v41
	v_mul_f32_e32 v20, v20, v21
	v_mul_f32_e32 v21, v28, v29
	v_mul_f32_e32 v28, v16, v17
	v_cvt_pk_bf16_f32 v16, v32, v20
	v_add_u32_e32 v32, 0xb0, v144
	v_mul_f32_e32 v31, v31, v38
	v_mul_f32_e32 v25, v25, v40
	v_mul_f32_e32 v22, v22, v23
	v_mul_f32_e32 v19, v18, v19
	v_cvt_pk_bf16_f32 v17, v21, v22
	v_ashrrev_i32_e32 v33, 31, v32
	v_mul_f32_e32 v23, v30, v31
	v_mul_f32_e32 v24, v24, v25
	v_cvt_pk_bf16_f32 v18, v23, v28
	v_cvt_pk_bf16_f32 v19, v24, v19
	global_store_dwordx4 v[26:27], v[16:19], off
	v_mov_b32_e32 v34, v12
	v_mov_b32_e32 v35, v4
	v_mov_b32_e32 v4, v13
	v_mov_b32_e32 v12, v14
	v_mov_b32_e32 v13, v6
	v_mov_b32_e32 v6, v15
	v_mov_b32_e32 v14, v8
	v_mov_b32_e32 v15, v0
	v_mov_b32_e32 v0, v9
	v_mov_b32_e32 v8, v10
	v_mov_b32_e32 v9, v2
	v_mov_b32_e32 v2, v11
	s_waitcnt vmcnt(1)
	v_pk_add_f32 v[236:237], v[236:237], v[238:239]
	v_pk_add_f32 v[240:241], v[240:241], v[242:243]
	v_pk_add_f32 v[244:245], v[244:245], v[246:247]
	v_pk_add_f32 v[248:249], v[248:249], v[250:251]
	v_pk_add_f32 v[236:237], v[236:237], v[240:241]
	v_pk_add_f32 v[244:245], v[244:245], v[248:249]
	s_nop 0
	v_pk_add_f32 v[236:237], v[236:237], v[244:245]
	s_nop 0
	v_add_f32_e32 v10, v236, v237
	v_fmamk_f32 v10, v10, 0x3a800000, v152
	v_mul_f32_e32 v11, 0x4b800000, v10
	v_cmp_gt_f32_e32 vcc, s73, v10
	s_nop 1
	v_cndmask_b32_e32 v10, v10, v11, vcc
	v_rsq_f32_e32 v16, v10
	v_mad_i64_i32 v[10:11], s[36:37], v32, s78, v[120:121]
	v_lshl_add_u64 v[10:11], v[10:11], 0, v[122:123]
	v_mul_f32_e32 v17, 0x45800000, v16
	v_cndmask_b32_e32 v16, v16, v17, vcc
	v_pk_mul_f32 v[2:3], v[2:3], v[16:17] op_sel_hi:[1,0]
	v_pk_mul_f32 v[18:19], v[34:35], v[16:17] op_sel_hi:[1,0]
	v_pk_mul_f32 v[4:5], v[4:5], v[16:17] op_sel_hi:[1,0]
	v_pk_mul_f32 v[12:13], v[12:13], v[16:17] op_sel_hi:[1,0]
	v_pk_mul_f32 v[6:7], v[6:7], v[16:17] op_sel_hi:[1,0]
	v_pk_mul_f32 v[14:15], v[14:15], v[16:17] op_sel_hi:[1,0]
	v_pk_mul_f32 v[0:1], v[0:1], v[16:17] op_sel_hi:[1,0]
	v_pk_mul_f32 v[8:9], v[8:9], v[16:17] op_sel_hi:[1,0]
	v_mul_f32_e32 v25, 0xbfb8aa3b, v3
	v_mul_f32_e32 v16, 0xbfb8aa3b, v19
	v_mul_f32_e32 v17, 0xbfb8aa3b, v5
	v_mul_f32_e32 v20, 0xbfb8aa3b, v13
	v_mul_f32_e32 v21, 0xbfb8aa3b, v7
	v_mul_f32_e32 v22, 0xbfb8aa3b, v15
	v_mul_f32_e32 v23, 0xbfb8aa3b, v1
	v_mul_f32_e32 v24, 0xbfb8aa3b, v9
	v_exp_f32_e32 v25, v25
	v_exp_f32_e32 v16, v16
	v_exp_f32_e32 v17, v17
	v_exp_f32_e32 v20, v20
	v_exp_f32_e32 v21, v21
	v_exp_f32_e32 v22, v22
	v_exp_f32_e32 v23, v23
	v_exp_f32_e32 v24, v24
	v_add_f32_e32 v25, 1.0, v25
	v_add_f32_e32 v16, 1.0, v16
	v_add_f32_e32 v17, 1.0, v17
	v_add_f32_e32 v20, 1.0, v20
	v_add_f32_e32 v21, 1.0, v21
	v_add_f32_e32 v22, 1.0, v22
	v_add_f32_e32 v23, 1.0, v23
	v_add_f32_e32 v24, 1.0, v24
	v_rcp_f32_e32 v25, v25
	v_rcp_f32_e32 v16, v16
	v_rcp_f32_e32 v17, v17
	v_rcp_f32_e32 v20, v20
	v_rcp_f32_e32 v21, v21
	v_rcp_f32_e32 v22, v22
	v_rcp_f32_e32 v23, v23
	v_rcp_f32_e32 v24, v24
	v_mul_f32_e32 v3, v3, v25
	v_mul_f32_e32 v16, v19, v16
	v_mul_f32_e32 v5, v5, v17
	v_mul_f32_e32 v13, v13, v20
	v_mul_f32_e32 v7, v7, v21
	v_mul_f32_e32 v15, v15, v22
	v_mul_f32_e32 v1, v1, v23
	v_mul_f32_e32 v9, v9, v24
	v_mul_f32_e32 v3, v2, v3
	s_andn2_b64 vcc, exec, s[14:15]
	s_mov_b64 s[14:15], -1
	v_mul_f32_e32 v16, v18, v16
	v_mul_f32_e32 v4, v4, v5
	v_mul_f32_e32 v5, v12, v13
	v_mul_f32_e32 v6, v6, v7
	v_mul_f32_e32 v7, v14, v15
	v_mul_f32_e32 v12, v0, v1
	v_mul_f32_e32 v8, v8, v9
	v_cvt_pk_bf16_f32 v0, v16, v4
	v_cvt_pk_bf16_f32 v1, v5, v6
	v_cvt_pk_bf16_f32 v2, v7, v12
	v_cvt_pk_bf16_f32 v3, v8, v3
	global_store_dwordx4 v[10:11], v[0:3], off
	s_cbranch_vccnz .LBB0_2016
	s_andn2_b64 vcc, exec, s[0:1]
	s_cbranch_vccnz .LBB0_2015
	s_barrier
	s_branch .LBB0_2015

.LBB0_3322:
	v_lshl_add_u32 v144, s24, 8, v146
	v_ashrrev_i32_e32 v145, 31, v144
	v_lshlrev_b64 v[154:155], 6, v[144:145]
	v_lshl_add_u64 v[166:167], s[10:11], 0, v[154:155]
	global_load_dwordx4 v[154:157], v[166:167], off
	global_load_dwordx4 v[158:161], v[166:167], off offset:16
	global_load_dwordx4 v[162:165], v[166:167], off offset:32
	s_nop 0
	global_load_dwordx4 v[166:169], v[166:167], off offset:48
	v_mov_b32_e32 v174, v122
	v_mov_b32_e32 v175, v114
	v_mov_b32_e32 v114, v123
	v_mov_b32_e32 v172, v124
	v_mov_b32_e32 v173, v116
	v_mov_b32_e32 v116, v125
	v_mov_b32_e32 v124, v126
	v_mov_b32_e32 v125, v118
	v_mov_b32_e32 v118, v127
	v_mov_b32_e32 v127, v112
	v_mov_b32_e32 v112, v121
	v_mov_b32_e32 v126, v120
	v_lshl_or_b32 v170, s54, 7, v148
	v_mov_b64_e32 v[120:121], s[8:9]
	v_ashrrev_i32_e32 v171, 31, v170
	s_waitcnt vmcnt(0)
	v_mov_b32_e32 v122, v155
	v_mov_b32_e32 v123, v156
	v_mov_b32_e32 v155, v157
	v_mov_b32_e32 v156, v159
	v_mov_b32_e32 v157, v160
	v_mov_b32_e32 v159, v161
	v_pk_add_f32 v[122:123], v[122:123], v[154:155]
	v_pk_add_f32 v[154:155], v[156:157], v[158:159]
	v_pk_add_f32 v[122:123], v[122:123], v[122:123] op_sel:[0,1] op_sel_hi:[1,0]
	v_pk_add_f32 v[154:155], v[154:155], v[154:155] op_sel:[0,1] op_sel_hi:[1,0]
	v_add_f32_e32 v160, v162, v163
	v_add_f32_e32 v162, v164, v165
	v_mov_b32_e32 v161, v168
	v_mov_b32_e32 v163, v169
	v_mov_b32_e32 v123, v166
	v_mov_b32_e32 v155, v167
	v_pk_add_f32 v[156:157], v[160:161], v[162:163]
	v_pk_add_f32 v[122:123], v[122:123], v[154:155]
	v_mad_i64_i32 v[154:155], s[26:27], v144, s53, v[120:121]
	v_pk_add_f32 v[122:123], v[122:123], v[156:157]
	s_nop 0
	v_add_f32_e32 v122, v122, v123
	v_or_b32_e32 v252, 16, v144
	v_ashrrev_i32_e32 v253, 31, v252
	v_lshlrev_b64 v[252:253], 6, v[252:253]
	v_lshl_add_u64 v[254:255], s[10:11], 0, v[252:253]
	global_load_dwordx4 v[236:239], v[254:255], off
	global_load_dwordx4 v[240:243], v[254:255], off offset:16
	global_load_dwordx4 v[244:247], v[254:255], off offset:32
	global_load_dwordx4 v[248:251], v[254:255], off offset:48
	v_fmamk_f32 v122, v122, 0x3a800000, v152
	v_mul_f32_e32 v123, 0x4b800000, v122
	v_cmp_gt_f32_e32 vcc, s52, v122
	s_nop 1
	v_cndmask_b32_e32 v122, v122, v123, vcc
	v_rsq_f32_e32 v145, v122
	v_lshlrev_b64 v[122:123], 1, v[170:171]
	v_lshl_add_u64 v[154:155], v[154:155], 0, v[122:123]
	v_mul_f32_e32 v153, 0x45800000, v145
	v_cndmask_b32_e32 v156, v145, v153, vcc
	v_pk_mul_f32 v[158:159], v[172:173], v[156:157] op_sel_hi:[1,0]
	v_pk_mul_f32 v[116:117], v[116:117], v[156:157] op_sel_hi:[1,0]
	v_pk_mul_f32 v[124:125], v[124:125], v[156:157] op_sel_hi:[1,0]
	v_pk_mul_f32 v[118:119], v[118:119], v[156:157] op_sel_hi:[1,0]
	v_pk_mul_f32 v[112:113], v[112:113], v[156:157] op_sel_hi:[1,0]
	v_pk_mul_f32 v[114:115], v[114:115], v[156:157] op_sel_hi:[1,0]
	v_mul_f32_e32 v145, 0xbfb8aa3b, v159
	v_pk_mul_f32 v[126:127], v[126:127], v[156:157] op_sel_hi:[1,0]
	v_pk_mul_f32 v[160:161], v[174:175], v[156:157] op_sel_hi:[1,0]
	v_mul_f32_e32 v153, 0xbfb8aa3b, v117
	v_mul_f32_e32 v156, 0xbfb8aa3b, v125
	v_mul_f32_e32 v157, 0xbfb8aa3b, v119
	v_mul_f32_e32 v163, 0xbfb8aa3b, v113
	v_mul_f32_e32 v165, 0xbfb8aa3b, v115
	v_exp_f32_e32 v145, v145
	v_mul_f32_e32 v162, 0xbfb8aa3b, v127
	v_mul_f32_e32 v164, 0xbfb8aa3b, v161
	v_exp_f32_e32 v153, v153
	v_exp_f32_e32 v156, v156
	v_exp_f32_e32 v157, v157
	v_exp_f32_e32 v163, v163
	v_exp_f32_e32 v165, v165
	v_exp_f32_e32 v162, v162
	v_exp_f32_e32 v164, v164
	v_add_f32_e32 v145, 1.0, v145
	v_add_f32_e32 v153, 1.0, v153
	v_add_f32_e32 v156, 1.0, v156
	v_add_f32_e32 v157, 1.0, v157
	v_add_f32_e32 v163, 1.0, v163
	v_add_f32_e32 v165, 1.0, v165
	v_rcp_f32_e32 v145, v145
	v_add_f32_e32 v162, 1.0, v162
	v_add_f32_e32 v164, 1.0, v164
	v_rcp_f32_e32 v153, v153
	v_rcp_f32_e32 v156, v156
	v_rcp_f32_e32 v157, v157
	v_rcp_f32_e32 v163, v163
	v_rcp_f32_e32 v165, v165
	v_rcp_f32_e32 v162, v162
	v_rcp_f32_e32 v164, v164
	v_mul_f32_e32 v145, v159, v145
	v_mul_f32_e32 v117, v117, v153
	v_mul_f32_e32 v125, v125, v156
	v_mul_f32_e32 v119, v119, v157
	v_mul_f32_e32 v113, v113, v163
	v_mul_f32_e32 v115, v115, v165
	v_mul_f32_e32 v145, v158, v145
	v_or_b32_e32 v158, 16, v144
	v_mul_f32_e32 v127, v127, v162
	v_mul_f32_e32 v153, v161, v164
	v_mul_f32_e32 v116, v116, v117
	v_mul_f32_e32 v117, v124, v125
	v_mul_f32_e32 v118, v118, v119
	v_mul_f32_e32 v124, v112, v113
	v_mul_f32_e32 v115, v114, v115
	v_cvt_pk_bf16_f32 v112, v145, v116
	v_cvt_pk_bf16_f32 v113, v117, v118
	v_ashrrev_i32_e32 v159, 31, v158
	v_mul_f32_e32 v119, v126, v127
	v_mul_f32_e32 v125, v160, v153
	v_cvt_pk_bf16_f32 v114, v119, v124
	v_cvt_pk_bf16_f32 v115, v125, v115
	global_store_dwordx4 v[154:155], v[112:115], off
	v_mov_b32_e32 v160, v108
	v_mov_b32_e32 v161, v100
	v_mov_b32_e32 v100, v109
	v_mov_b32_e32 v108, v110
	v_mov_b32_e32 v109, v102
	v_mov_b32_e32 v102, v111
	v_mov_b32_e32 v110, v104
	v_mov_b32_e32 v111, v96
	v_mov_b32_e32 v96, v105
	v_mov_b32_e32 v104, v106
	v_mov_b32_e32 v105, v98
	v_mov_b32_e32 v98, v107
	s_waitcnt vmcnt(1)
	v_pk_add_f32 v[236:237], v[236:237], v[238:239]
	v_pk_add_f32 v[240:241], v[240:241], v[242:243]
	v_pk_add_f32 v[244:245], v[244:245], v[246:247]
	v_pk_add_f32 v[248:249], v[248:249], v[250:251]
	v_pk_add_f32 v[236:237], v[236:237], v[240:241]
	v_pk_add_f32 v[244:245], v[244:245], v[248:249]
	s_nop 0
	v_pk_add_f32 v[236:237], v[236:237], v[244:245]
	s_nop 0
	v_add_f32_e32 v106, v236, v237
	v_or_b32_e32 v252, 32, v144
	v_ashrrev_i32_e32 v253, 31, v252
	v_lshlrev_b64 v[252:253], 6, v[252:253]
	v_lshl_add_u64 v[254:255], s[10:11], 0, v[252:253]
	global_load_dwordx4 v[236:239], v[254:255], off
	global_load_dwordx4 v[240:243], v[254:255], off offset:16
	global_load_dwordx4 v[244:247], v[254:255], off offset:32
	global_load_dwordx4 v[248:251], v[254:255], off offset:48
	v_fmamk_f32 v106, v106, 0x3a800000, v152
	v_mul_f32_e32 v107, 0x4b800000, v106
	v_cmp_gt_f32_e32 vcc, s52, v106
	s_nop 1
	v_cndmask_b32_e32 v106, v106, v107, vcc
	v_rsq_f32_e32 v112, v106
	v_mad_i64_i32 v[106:107], s[26:27], v158, s53, v[120:121]
	v_lshl_add_u64 v[106:107], v[106:107], 0, v[122:123]
	v_mul_f32_e32 v113, 0x45800000, v112
	v_cndmask_b32_e32 v112, v112, v113, vcc
	v_pk_mul_f32 v[114:115], v[160:161], v[112:113] op_sel_hi:[1,0]
	v_pk_mul_f32 v[100:101], v[100:101], v[112:113] op_sel_hi:[1,0]
	v_pk_mul_f32 v[108:109], v[108:109], v[112:113] op_sel_hi:[1,0]
	v_pk_mul_f32 v[102:103], v[102:103], v[112:113] op_sel_hi:[1,0]
	v_pk_mul_f32 v[110:111], v[110:111], v[112:113] op_sel_hi:[1,0]
	v_pk_mul_f32 v[96:97], v[96:97], v[112:113] op_sel_hi:[1,0]
	v_pk_mul_f32 v[104:105], v[104:105], v[112:113] op_sel_hi:[1,0]
	v_pk_mul_f32 v[98:99], v[98:99], v[112:113] op_sel_hi:[1,0]
	v_mul_f32_e32 v112, 0xbfb8aa3b, v115
	v_mul_f32_e32 v113, 0xbfb8aa3b, v101
	v_mul_f32_e32 v116, 0xbfb8aa3b, v109
	v_mul_f32_e32 v119, 0xbfb8aa3b, v97
	v_exp_f32_e32 v112, v112
	v_mul_f32_e32 v117, 0xbfb8aa3b, v103
	v_mul_f32_e32 v125, 0xbfb8aa3b, v99
	v_exp_f32_e32 v113, v113
	v_exp_f32_e32 v116, v116
	v_exp_f32_e32 v119, v119
	v_mul_f32_e32 v118, 0xbfb8aa3b, v111
	v_mul_f32_e32 v124, 0xbfb8aa3b, v105
	v_exp_f32_e32 v117, v117
	v_exp_f32_e32 v125, v125
	v_exp_f32_e32 v118, v118
	v_exp_f32_e32 v124, v124
	v_add_f32_e32 v112, 1.0, v112
	v_add_f32_e32 v113, 1.0, v113
	v_add_f32_e32 v116, 1.0, v116
	v_add_f32_e32 v119, 1.0, v119
	v_rcp_f32_e32 v112, v112
	v_add_f32_e32 v117, 1.0, v117
	v_add_f32_e32 v125, 1.0, v125
	v_rcp_f32_e32 v113, v113
	v_rcp_f32_e32 v116, v116
	v_rcp_f32_e32 v119, v119
	v_add_f32_e32 v118, 1.0, v118
	v_add_f32_e32 v124, 1.0, v124
	v_rcp_f32_e32 v117, v117
	v_rcp_f32_e32 v125, v125
	v_rcp_f32_e32 v118, v118
	v_rcp_f32_e32 v124, v124
	v_mul_f32_e32 v112, v115, v112
	v_mul_f32_e32 v101, v101, v113
	v_mul_f32_e32 v109, v109, v116
	v_mul_f32_e32 v97, v97, v119
	v_mul_f32_e32 v112, v114, v112
	v_mul_f32_e32 v103, v103, v117
	v_mul_f32_e32 v99, v99, v125
	v_mul_f32_e32 v100, v100, v101
	v_mul_f32_e32 v101, v108, v109
	v_mul_f32_e32 v108, v96, v97
	v_cvt_pk_bf16_f32 v96, v112, v100
	v_or_b32_e32 v112, 32, v144
	v_mul_f32_e32 v111, v111, v118
	v_mul_f32_e32 v105, v105, v124
	v_mul_f32_e32 v102, v102, v103
	v_mul_f32_e32 v99, v98, v99
	v_cvt_pk_bf16_f32 v97, v101, v102
	v_ashrrev_i32_e32 v113, 31, v112
	v_mul_f32_e32 v103, v110, v111
	v_mul_f32_e32 v104, v104, v105
	v_cvt_pk_bf16_f32 v98, v103, v108
	v_cvt_pk_bf16_f32 v99, v104, v99
	global_store_dwordx4 v[106:107], v[96:99], off
	v_mov_b32_e32 v114, v92
	v_mov_b32_e32 v115, v84
	v_mov_b32_e32 v84, v93
	v_mov_b32_e32 v92, v94
	v_mov_b32_e32 v93, v86
	v_mov_b32_e32 v86, v95
	v_mov_b32_e32 v94, v88
	v_mov_b32_e32 v95, v80
	v_mov_b32_e32 v80, v89
	v_mov_b32_e32 v88, v90
	v_mov_b32_e32 v89, v82
	v_mov_b32_e32 v82, v91
	s_waitcnt vmcnt(1)
	v_pk_add_f32 v[236:237], v[236:237], v[238:239]
	v_pk_add_f32 v[240:241], v[240:241], v[242:243]
	v_pk_add_f32 v[244:245], v[244:245], v[246:247]
	v_pk_add_f32 v[248:249], v[248:249], v[250:251]
	v_pk_add_f32 v[236:237], v[236:237], v[240:241]
	v_pk_add_f32 v[244:245], v[244:245], v[248:249]
	s_nop 0
	v_pk_add_f32 v[236:237], v[236:237], v[244:245]
	s_nop 0
	v_add_f32_e32 v90, v236, v237
	v_or_b32_e32 v252, 48, v144
	v_ashrrev_i32_e32 v253, 31, v252
	v_lshlrev_b64 v[252:253], 6, v[252:253]
	v_lshl_add_u64 v[254:255], s[10:11], 0, v[252:253]
	global_load_dwordx4 v[236:239], v[254:255], off
	global_load_dwordx4 v[240:243], v[254:255], off offset:16
	global_load_dwordx4 v[244:247], v[254:255], off offset:32
	global_load_dwordx4 v[248:251], v[254:255], off offset:48
	v_fmamk_f32 v90, v90, 0x3a800000, v152
	v_mul_f32_e32 v91, 0x4b800000, v90
	v_cmp_gt_f32_e32 vcc, s52, v90
	s_nop 1
	v_cndmask_b32_e32 v90, v90, v91, vcc
	v_rsq_f32_e32 v96, v90
	v_mad_i64_i32 v[90:91], s[26:27], v112, s53, v[120:121]
	v_lshl_add_u64 v[90:91], v[90:91], 0, v[122:123]
	v_mul_f32_e32 v97, 0x45800000, v96
	v_cndmask_b32_e32 v96, v96, v97, vcc
	v_pk_mul_f32 v[98:99], v[114:115], v[96:97] op_sel_hi:[1,0]
	v_pk_mul_f32 v[84:85], v[84:85], v[96:97] op_sel_hi:[1,0]
	v_pk_mul_f32 v[92:93], v[92:93], v[96:97] op_sel_hi:[1,0]
	v_pk_mul_f32 v[86:87], v[86:87], v[96:97] op_sel_hi:[1,0]
	v_pk_mul_f32 v[94:95], v[94:95], v[96:97] op_sel_hi:[1,0]
	v_pk_mul_f32 v[80:81], v[80:81], v[96:97] op_sel_hi:[1,0]
	v_pk_mul_f32 v[88:89], v[88:89], v[96:97] op_sel_hi:[1,0]
	v_pk_mul_f32 v[82:83], v[82:83], v[96:97] op_sel_hi:[1,0]
	v_mul_f32_e32 v96, 0xbfb8aa3b, v99
	v_mul_f32_e32 v97, 0xbfb8aa3b, v85
	v_mul_f32_e32 v100, 0xbfb8aa3b, v93
	v_mul_f32_e32 v103, 0xbfb8aa3b, v81
	v_exp_f32_e32 v96, v96
	v_mul_f32_e32 v101, 0xbfb8aa3b, v87
	v_mul_f32_e32 v105, 0xbfb8aa3b, v83
	v_exp_f32_e32 v97, v97
	v_exp_f32_e32 v100, v100
	v_exp_f32_e32 v103, v103
	v_mul_f32_e32 v102, 0xbfb8aa3b, v95
	v_mul_f32_e32 v104, 0xbfb8aa3b, v89
	v_exp_f32_e32 v101, v101
	v_exp_f32_e32 v105, v105
	v_exp_f32_e32 v102, v102
	v_exp_f32_e32 v104, v104
	v_add_f32_e32 v96, 1.0, v96
	v_add_f32_e32 v97, 1.0, v97
	v_add_f32_e32 v100, 1.0, v100
	v_add_f32_e32 v103, 1.0, v103
	v_rcp_f32_e32 v96, v96
	v_add_f32_e32 v101, 1.0, v101
	v_add_f32_e32 v105, 1.0, v105
	v_rcp_f32_e32 v97, v97
	v_rcp_f32_e32 v100, v100
	v_rcp_f32_e32 v103, v103
	v_add_f32_e32 v102, 1.0, v102
	v_add_f32_e32 v104, 1.0, v104
	v_rcp_f32_e32 v101, v101
	v_rcp_f32_e32 v105, v105
	v_rcp_f32_e32 v102, v102
	v_rcp_f32_e32 v104, v104
	v_mul_f32_e32 v96, v99, v96
	v_mul_f32_e32 v85, v85, v97
	v_mul_f32_e32 v93, v93, v100
	v_mul_f32_e32 v81, v81, v103
	v_mul_f32_e32 v96, v98, v96
	v_mul_f32_e32 v87, v87, v101
	v_mul_f32_e32 v83, v83, v105
	v_mul_f32_e32 v84, v84, v85
	v_mul_f32_e32 v85, v92, v93
	v_mul_f32_e32 v92, v80, v81
	v_cvt_pk_bf16_f32 v80, v96, v84
	v_or_b32_e32 v96, 48, v144
	v_mul_f32_e32 v95, v95, v102
	v_mul_f32_e32 v89, v89, v104
	v_mul_f32_e32 v86, v86, v87
	v_mul_f32_e32 v83, v82, v83
	v_cvt_pk_bf16_f32 v81, v85, v86
	v_ashrrev_i32_e32 v97, 31, v96
	v_mul_f32_e32 v87, v94, v95
	v_mul_f32_e32 v88, v88, v89
	v_cvt_pk_bf16_f32 v82, v87, v92
	v_cvt_pk_bf16_f32 v83, v88, v83
	global_store_dwordx4 v[90:91], v[80:83], off
	v_mov_b32_e32 v98, v76
	v_mov_b32_e32 v99, v68
	v_mov_b32_e32 v68, v77
	v_mov_b32_e32 v76, v78
	v_mov_b32_e32 v77, v70
	v_mov_b32_e32 v70, v79
	v_mov_b32_e32 v78, v72
	v_mov_b32_e32 v79, v64
	v_mov_b32_e32 v64, v73
	v_mov_b32_e32 v72, v74
	v_mov_b32_e32 v73, v66
	v_mov_b32_e32 v66, v75
	s_waitcnt vmcnt(1)
	v_pk_add_f32 v[236:237], v[236:237], v[238:239]
	v_pk_add_f32 v[240:241], v[240:241], v[242:243]
	v_pk_add_f32 v[244:245], v[244:245], v[246:247]
	v_pk_add_f32 v[248:249], v[248:249], v[250:251]
	v_pk_add_f32 v[236:237], v[236:237], v[240:241]
	v_pk_add_f32 v[244:245], v[244:245], v[248:249]
	s_nop 0
	v_pk_add_f32 v[236:237], v[236:237], v[244:245]
	s_nop 0
	v_add_f32_e32 v74, v236, v237
	v_add_u32_e32 v252, 0x80, v144
	v_ashrrev_i32_e32 v253, 31, v252
	v_lshlrev_b64 v[252:253], 6, v[252:253]
	v_lshl_add_u64 v[254:255], s[10:11], 0, v[252:253]
	global_load_dwordx4 v[236:239], v[254:255], off
	global_load_dwordx4 v[240:243], v[254:255], off offset:16
	global_load_dwordx4 v[244:247], v[254:255], off offset:32
	global_load_dwordx4 v[248:251], v[254:255], off offset:48
	v_fmamk_f32 v74, v74, 0x3a800000, v152
	v_mul_f32_e32 v75, 0x4b800000, v74
	v_cmp_gt_f32_e32 vcc, s52, v74
	s_nop 1
	v_cndmask_b32_e32 v74, v74, v75, vcc
	v_rsq_f32_e32 v80, v74
	v_mad_i64_i32 v[74:75], s[26:27], v96, s53, v[120:121]
	v_lshl_add_u64 v[74:75], v[74:75], 0, v[122:123]
	v_mul_f32_e32 v81, 0x45800000, v80
	v_cndmask_b32_e32 v80, v80, v81, vcc
	v_pk_mul_f32 v[82:83], v[98:99], v[80:81] op_sel_hi:[1,0]
	v_pk_mul_f32 v[68:69], v[68:69], v[80:81] op_sel_hi:[1,0]
	v_pk_mul_f32 v[76:77], v[76:77], v[80:81] op_sel_hi:[1,0]
	v_pk_mul_f32 v[70:71], v[70:71], v[80:81] op_sel_hi:[1,0]
	v_pk_mul_f32 v[78:79], v[78:79], v[80:81] op_sel_hi:[1,0]
	v_pk_mul_f32 v[64:65], v[64:65], v[80:81] op_sel_hi:[1,0]
	v_pk_mul_f32 v[72:73], v[72:73], v[80:81] op_sel_hi:[1,0]
	v_pk_mul_f32 v[66:67], v[66:67], v[80:81] op_sel_hi:[1,0]
	v_mul_f32_e32 v80, 0xbfb8aa3b, v83
	v_mul_f32_e32 v81, 0xbfb8aa3b, v69
	v_mul_f32_e32 v84, 0xbfb8aa3b, v77
	v_mul_f32_e32 v87, 0xbfb8aa3b, v65
	v_exp_f32_e32 v80, v80
	v_mul_f32_e32 v85, 0xbfb8aa3b, v71
	v_mul_f32_e32 v89, 0xbfb8aa3b, v67
	v_exp_f32_e32 v81, v81
	v_exp_f32_e32 v84, v84
	v_exp_f32_e32 v87, v87
	v_mul_f32_e32 v86, 0xbfb8aa3b, v79
	v_mul_f32_e32 v88, 0xbfb8aa3b, v73
	v_exp_f32_e32 v85, v85
	v_exp_f32_e32 v89, v89
	v_exp_f32_e32 v86, v86
	v_exp_f32_e32 v88, v88
	v_add_f32_e32 v80, 1.0, v80
	v_add_f32_e32 v81, 1.0, v81
	v_add_f32_e32 v84, 1.0, v84
	v_add_f32_e32 v87, 1.0, v87
	v_rcp_f32_e32 v80, v80
	v_add_f32_e32 v85, 1.0, v85
	v_add_f32_e32 v89, 1.0, v89
	v_rcp_f32_e32 v81, v81
	v_rcp_f32_e32 v84, v84
	v_rcp_f32_e32 v87, v87
	v_add_f32_e32 v86, 1.0, v86
	v_add_f32_e32 v88, 1.0, v88
	v_rcp_f32_e32 v85, v85
	v_rcp_f32_e32 v89, v89
	v_rcp_f32_e32 v86, v86
	v_rcp_f32_e32 v88, v88
	v_mul_f32_e32 v80, v83, v80
	v_mul_f32_e32 v69, v69, v81
	v_mul_f32_e32 v77, v77, v84
	v_mul_f32_e32 v65, v65, v87
	v_mul_f32_e32 v80, v82, v80
	v_mul_f32_e32 v71, v71, v85
	v_mul_f32_e32 v67, v67, v89
	v_mul_f32_e32 v68, v68, v69
	v_mul_f32_e32 v69, v76, v77
	v_mul_f32_e32 v76, v64, v65
	v_cvt_pk_bf16_f32 v64, v80, v68
	v_add_u32_e32 v80, 0x80, v144
	v_mul_f32_e32 v79, v79, v86
	v_mul_f32_e32 v73, v73, v88
	v_mul_f32_e32 v70, v70, v71
	v_mul_f32_e32 v67, v66, v67
	v_cvt_pk_bf16_f32 v65, v69, v70
	v_ashrrev_i32_e32 v81, 31, v80
	v_mul_f32_e32 v71, v78, v79
	v_mul_f32_e32 v72, v72, v73
	v_cvt_pk_bf16_f32 v66, v71, v76
	v_cvt_pk_bf16_f32 v67, v72, v67
	global_store_dwordx4 v[74:75], v[64:67], off
	v_mov_b32_e32 v82, v60
	v_mov_b32_e32 v83, v52
	v_mov_b32_e32 v52, v61
	v_mov_b32_e32 v60, v62
	v_mov_b32_e32 v61, v54
	v_mov_b32_e32 v54, v63
	v_mov_b32_e32 v62, v56
	v_mov_b32_e32 v63, v48
	v_mov_b32_e32 v48, v57
	v_mov_b32_e32 v56, v58
	v_mov_b32_e32 v57, v50
	v_mov_b32_e32 v50, v59
	s_waitcnt vmcnt(1)
	v_pk_add_f32 v[236:237], v[236:237], v[238:239]
	v_pk_add_f32 v[240:241], v[240:241], v[242:243]
	v_pk_add_f32 v[244:245], v[244:245], v[246:247]
	v_pk_add_f32 v[248:249], v[248:249], v[250:251]
	v_pk_add_f32 v[236:237], v[236:237], v[240:241]
	v_pk_add_f32 v[244:245], v[244:245], v[248:249]
	s_nop 0
	v_pk_add_f32 v[236:237], v[236:237], v[244:245]
	s_nop 0
	v_add_f32_e32 v58, v236, v237
	v_add_u32_e32 v252, 0x90, v144
	v_ashrrev_i32_e32 v253, 31, v252
	v_lshlrev_b64 v[252:253], 6, v[252:253]
	v_lshl_add_u64 v[254:255], s[10:11], 0, v[252:253]
	global_load_dwordx4 v[236:239], v[254:255], off
	global_load_dwordx4 v[240:243], v[254:255], off offset:16
	global_load_dwordx4 v[244:247], v[254:255], off offset:32
	global_load_dwordx4 v[248:251], v[254:255], off offset:48
	v_fmamk_f32 v58, v58, 0x3a800000, v152
	v_mul_f32_e32 v59, 0x4b800000, v58
	v_cmp_gt_f32_e32 vcc, s52, v58
	s_nop 1
	v_cndmask_b32_e32 v58, v58, v59, vcc
	v_rsq_f32_e32 v64, v58
	v_mad_i64_i32 v[58:59], s[26:27], v80, s53, v[120:121]
	v_lshl_add_u64 v[58:59], v[58:59], 0, v[122:123]
	v_mul_f32_e32 v65, 0x45800000, v64
	v_cndmask_b32_e32 v64, v64, v65, vcc
	v_pk_mul_f32 v[66:67], v[82:83], v[64:65] op_sel_hi:[1,0]
	v_pk_mul_f32 v[52:53], v[52:53], v[64:65] op_sel_hi:[1,0]
	v_pk_mul_f32 v[60:61], v[60:61], v[64:65] op_sel_hi:[1,0]
	v_pk_mul_f32 v[54:55], v[54:55], v[64:65] op_sel_hi:[1,0]
	v_pk_mul_f32 v[62:63], v[62:63], v[64:65] op_sel_hi:[1,0]
	v_pk_mul_f32 v[48:49], v[48:49], v[64:65] op_sel_hi:[1,0]
	v_pk_mul_f32 v[56:57], v[56:57], v[64:65] op_sel_hi:[1,0]
	v_pk_mul_f32 v[50:51], v[50:51], v[64:65] op_sel_hi:[1,0]
	v_mul_f32_e32 v64, 0xbfb8aa3b, v67
	v_mul_f32_e32 v65, 0xbfb8aa3b, v53
	v_mul_f32_e32 v68, 0xbfb8aa3b, v61
	v_mul_f32_e32 v71, 0xbfb8aa3b, v49
	v_exp_f32_e32 v64, v64
	v_mul_f32_e32 v69, 0xbfb8aa3b, v55
	v_mul_f32_e32 v73, 0xbfb8aa3b, v51
	v_exp_f32_e32 v65, v65
	v_exp_f32_e32 v68, v68
	v_exp_f32_e32 v71, v71
	v_mul_f32_e32 v70, 0xbfb8aa3b, v63
	v_mul_f32_e32 v72, 0xbfb8aa3b, v57
	v_exp_f32_e32 v69, v69
	v_exp_f32_e32 v73, v73
	v_exp_f32_e32 v70, v70
	v_exp_f32_e32 v72, v72
	v_add_f32_e32 v64, 1.0, v64
	v_add_f32_e32 v65, 1.0, v65
	v_add_f32_e32 v68, 1.0, v68
	v_add_f32_e32 v71, 1.0, v71
	v_rcp_f32_e32 v64, v64
	v_add_f32_e32 v69, 1.0, v69
	v_add_f32_e32 v73, 1.0, v73
	v_rcp_f32_e32 v65, v65
	v_rcp_f32_e32 v68, v68
	v_rcp_f32_e32 v71, v71
	v_add_f32_e32 v70, 1.0, v70
	v_add_f32_e32 v72, 1.0, v72
	v_rcp_f32_e32 v69, v69
	v_rcp_f32_e32 v73, v73
	v_rcp_f32_e32 v70, v70
	v_rcp_f32_e32 v72, v72
	v_mul_f32_e32 v64, v67, v64
	v_mul_f32_e32 v53, v53, v65
	v_mul_f32_e32 v61, v61, v68
	v_mul_f32_e32 v49, v49, v71
	v_mul_f32_e32 v64, v66, v64
	v_mul_f32_e32 v55, v55, v69
	v_mul_f32_e32 v51, v51, v73
	v_mul_f32_e32 v52, v52, v53
	v_mul_f32_e32 v53, v60, v61
	v_mul_f32_e32 v60, v48, v49
	v_cvt_pk_bf16_f32 v48, v64, v52
	v_add_u32_e32 v64, 0x90, v144
	v_mul_f32_e32 v63, v63, v70
	v_mul_f32_e32 v57, v57, v72
	v_mul_f32_e32 v54, v54, v55
	v_mul_f32_e32 v51, v50, v51
	v_cvt_pk_bf16_f32 v49, v53, v54
	v_ashrrev_i32_e32 v65, 31, v64
	v_mul_f32_e32 v55, v62, v63
	v_mul_f32_e32 v56, v56, v57
	v_cvt_pk_bf16_f32 v50, v55, v60
	v_cvt_pk_bf16_f32 v51, v56, v51
	global_store_dwordx4 v[58:59], v[48:51], off
	v_mov_b32_e32 v66, v44
	v_mov_b32_e32 v67, v36
	v_mov_b32_e32 v36, v45
	v_mov_b32_e32 v44, v46
	v_mov_b32_e32 v45, v38
	v_mov_b32_e32 v38, v47
	v_mov_b32_e32 v46, v40
	v_mov_b32_e32 v47, v32
	v_mov_b32_e32 v32, v41
	v_mov_b32_e32 v40, v42
	v_mov_b32_e32 v41, v34
	v_mov_b32_e32 v34, v43
	s_waitcnt vmcnt(1)
	v_pk_add_f32 v[236:237], v[236:237], v[238:239]
	v_pk_add_f32 v[240:241], v[240:241], v[242:243]
	v_pk_add_f32 v[244:245], v[244:245], v[246:247]
	v_pk_add_f32 v[248:249], v[248:249], v[250:251]
	v_pk_add_f32 v[236:237], v[236:237], v[240:241]
	v_pk_add_f32 v[244:245], v[244:245], v[248:249]
	s_nop 0
	v_pk_add_f32 v[236:237], v[236:237], v[244:245]
	s_nop 0
	v_add_f32_e32 v42, v236, v237
	v_add_u32_e32 v252, 0xa0, v144
	v_ashrrev_i32_e32 v253, 31, v252
	v_lshlrev_b64 v[252:253], 6, v[252:253]
	v_lshl_add_u64 v[254:255], s[10:11], 0, v[252:253]
	global_load_dwordx4 v[236:239], v[254:255], off
	global_load_dwordx4 v[240:243], v[254:255], off offset:16
	global_load_dwordx4 v[244:247], v[254:255], off offset:32
	global_load_dwordx4 v[248:251], v[254:255], off offset:48
	v_fmamk_f32 v42, v42, 0x3a800000, v152
	v_mul_f32_e32 v43, 0x4b800000, v42
	v_cmp_gt_f32_e32 vcc, s52, v42
	s_nop 1
	v_cndmask_b32_e32 v42, v42, v43, vcc
	v_rsq_f32_e32 v48, v42
	v_mad_i64_i32 v[42:43], s[26:27], v64, s53, v[120:121]
	v_lshl_add_u64 v[42:43], v[42:43], 0, v[122:123]
	v_mul_f32_e32 v49, 0x45800000, v48
	v_cndmask_b32_e32 v48, v48, v49, vcc
	v_pk_mul_f32 v[50:51], v[66:67], v[48:49] op_sel_hi:[1,0]
	v_pk_mul_f32 v[36:37], v[36:37], v[48:49] op_sel_hi:[1,0]
	v_pk_mul_f32 v[44:45], v[44:45], v[48:49] op_sel_hi:[1,0]
	v_pk_mul_f32 v[38:39], v[38:39], v[48:49] op_sel_hi:[1,0]
	v_pk_mul_f32 v[46:47], v[46:47], v[48:49] op_sel_hi:[1,0]
	v_pk_mul_f32 v[32:33], v[32:33], v[48:49] op_sel_hi:[1,0]
	v_pk_mul_f32 v[40:41], v[40:41], v[48:49] op_sel_hi:[1,0]
	v_pk_mul_f32 v[34:35], v[34:35], v[48:49] op_sel_hi:[1,0]
	v_mul_f32_e32 v48, 0xbfb8aa3b, v51
	v_mul_f32_e32 v49, 0xbfb8aa3b, v37
	v_mul_f32_e32 v52, 0xbfb8aa3b, v45
	v_mul_f32_e32 v55, 0xbfb8aa3b, v33
	v_exp_f32_e32 v48, v48
	v_mul_f32_e32 v53, 0xbfb8aa3b, v39
	v_mul_f32_e32 v57, 0xbfb8aa3b, v35
	v_exp_f32_e32 v49, v49
	v_exp_f32_e32 v52, v52
	v_exp_f32_e32 v55, v55
	v_mul_f32_e32 v54, 0xbfb8aa3b, v47
	v_mul_f32_e32 v56, 0xbfb8aa3b, v41
	v_exp_f32_e32 v53, v53
	v_exp_f32_e32 v57, v57
	v_exp_f32_e32 v54, v54
	v_exp_f32_e32 v56, v56
	v_add_f32_e32 v48, 1.0, v48
	v_add_f32_e32 v49, 1.0, v49
	v_add_f32_e32 v52, 1.0, v52
	v_add_f32_e32 v55, 1.0, v55
	v_rcp_f32_e32 v48, v48
	v_add_f32_e32 v53, 1.0, v53
	v_add_f32_e32 v57, 1.0, v57
	v_rcp_f32_e32 v49, v49
	v_rcp_f32_e32 v52, v52
	v_rcp_f32_e32 v55, v55
	v_add_f32_e32 v54, 1.0, v54
	v_add_f32_e32 v56, 1.0, v56
	v_rcp_f32_e32 v53, v53
	v_rcp_f32_e32 v57, v57
	v_rcp_f32_e32 v54, v54
	v_rcp_f32_e32 v56, v56
	v_mul_f32_e32 v48, v51, v48
	v_mul_f32_e32 v37, v37, v49
	v_mul_f32_e32 v45, v45, v52
	v_mul_f32_e32 v33, v33, v55
	v_mul_f32_e32 v48, v50, v48
	v_mul_f32_e32 v39, v39, v53
	v_mul_f32_e32 v35, v35, v57
	v_mul_f32_e32 v36, v36, v37
	v_mul_f32_e32 v37, v44, v45
	v_mul_f32_e32 v44, v32, v33
	v_cvt_pk_bf16_f32 v32, v48, v36
	v_add_u32_e32 v48, 0xa0, v144
	v_mul_f32_e32 v47, v47, v54
	v_mul_f32_e32 v41, v41, v56
	v_mul_f32_e32 v38, v38, v39
	v_mul_f32_e32 v35, v34, v35
	v_cvt_pk_bf16_f32 v33, v37, v38
	v_ashrrev_i32_e32 v49, 31, v48
	v_mul_f32_e32 v39, v46, v47
	v_mul_f32_e32 v40, v40, v41
	v_cvt_pk_bf16_f32 v34, v39, v44
	v_cvt_pk_bf16_f32 v35, v40, v35
	global_store_dwordx4 v[42:43], v[32:35], off
	v_mov_b32_e32 v50, v28
	v_mov_b32_e32 v51, v20
	v_mov_b32_e32 v20, v29
	v_mov_b32_e32 v28, v30
	v_mov_b32_e32 v29, v22
	v_mov_b32_e32 v22, v31
	v_mov_b32_e32 v30, v24
	v_mov_b32_e32 v31, v16
	v_mov_b32_e32 v16, v25
	v_mov_b32_e32 v24, v26
	v_mov_b32_e32 v25, v18
	v_mov_b32_e32 v18, v27
	s_waitcnt vmcnt(1)
	v_pk_add_f32 v[236:237], v[236:237], v[238:239]
	v_pk_add_f32 v[240:241], v[240:241], v[242:243]
	v_pk_add_f32 v[244:245], v[244:245], v[246:247]
	v_pk_add_f32 v[248:249], v[248:249], v[250:251]
	v_pk_add_f32 v[236:237], v[236:237], v[240:241]
	v_pk_add_f32 v[244:245], v[244:245], v[248:249]
	s_nop 0
	v_pk_add_f32 v[236:237], v[236:237], v[244:245]
	s_nop 0
	v_add_f32_e32 v26, v236, v237
	v_add_u32_e32 v252, 0xb0, v144
	v_ashrrev_i32_e32 v253, 31, v252
	v_lshlrev_b64 v[252:253], 6, v[252:253]
	v_lshl_add_u64 v[254:255], s[10:11], 0, v[252:253]
	global_load_dwordx4 v[236:239], v[254:255], off
	global_load_dwordx4 v[240:243], v[254:255], off offset:16
	global_load_dwordx4 v[244:247], v[254:255], off offset:32
	global_load_dwordx4 v[248:251], v[254:255], off offset:48
	v_fmamk_f32 v26, v26, 0x3a800000, v152
	v_mul_f32_e32 v27, 0x4b800000, v26
	v_cmp_gt_f32_e32 vcc, s52, v26
	s_nop 1
	v_cndmask_b32_e32 v26, v26, v27, vcc
	v_rsq_f32_e32 v32, v26
	v_mad_i64_i32 v[26:27], s[26:27], v48, s53, v[120:121]
	v_lshl_add_u64 v[26:27], v[26:27], 0, v[122:123]
	v_mul_f32_e32 v33, 0x45800000, v32
	v_cndmask_b32_e32 v32, v32, v33, vcc
	v_pk_mul_f32 v[34:35], v[50:51], v[32:33] op_sel_hi:[1,0]
	v_pk_mul_f32 v[20:21], v[20:21], v[32:33] op_sel_hi:[1,0]
	v_pk_mul_f32 v[28:29], v[28:29], v[32:33] op_sel_hi:[1,0]
	v_pk_mul_f32 v[22:23], v[22:23], v[32:33] op_sel_hi:[1,0]
	v_pk_mul_f32 v[30:31], v[30:31], v[32:33] op_sel_hi:[1,0]
	v_pk_mul_f32 v[16:17], v[16:17], v[32:33] op_sel_hi:[1,0]
	v_pk_mul_f32 v[24:25], v[24:25], v[32:33] op_sel_hi:[1,0]
	v_pk_mul_f32 v[18:19], v[18:19], v[32:33] op_sel_hi:[1,0]
	v_mul_f32_e32 v32, 0xbfb8aa3b, v35
	v_mul_f32_e32 v33, 0xbfb8aa3b, v21
	v_mul_f32_e32 v36, 0xbfb8aa3b, v29
	v_mul_f32_e32 v39, 0xbfb8aa3b, v17
	v_exp_f32_e32 v32, v32
	v_mul_f32_e32 v37, 0xbfb8aa3b, v23
	v_mul_f32_e32 v41, 0xbfb8aa3b, v19
	v_exp_f32_e32 v33, v33
	v_exp_f32_e32 v36, v36
	v_exp_f32_e32 v39, v39
	v_mul_f32_e32 v38, 0xbfb8aa3b, v31
	v_mul_f32_e32 v40, 0xbfb8aa3b, v25
	v_exp_f32_e32 v37, v37
	v_exp_f32_e32 v41, v41
	v_exp_f32_e32 v38, v38
	v_exp_f32_e32 v40, v40
	v_add_f32_e32 v32, 1.0, v32
	v_add_f32_e32 v33, 1.0, v33
	v_add_f32_e32 v36, 1.0, v36
	v_add_f32_e32 v39, 1.0, v39
	v_rcp_f32_e32 v32, v32
	v_add_f32_e32 v37, 1.0, v37
	v_add_f32_e32 v41, 1.0, v41
	v_rcp_f32_e32 v33, v33
	v_rcp_f32_e32 v36, v36
	v_rcp_f32_e32 v39, v39
	v_add_f32_e32 v38, 1.0, v38
	v_add_f32_e32 v40, 1.0, v40
	v_rcp_f32_e32 v37, v37
	v_rcp_f32_e32 v41, v41
	v_rcp_f32_e32 v38, v38
	v_rcp_f32_e32 v40, v40
	v_mul_f32_e32 v32, v35, v32
	v_mul_f32_e32 v21, v21, v33
	v_mul_f32_e32 v29, v29, v36
	v_mul_f32_e32 v17, v17, v39
	v_mul_f32_e32 v32, v34, v32
	v_mul_f32_e32 v23, v23, v37
	v_mul_f32_e32 v19, v19, v41
	v_mul_f32_e32 v20, v20, v21
	v_mul_f32_e32 v21, v28, v29
	v_mul_f32_e32 v28, v16, v17
	v_cvt_pk_bf16_f32 v16, v32, v20
	v_add_u32_e32 v32, 0xb0, v144
	v_mul_f32_e32 v31, v31, v38
	v_mul_f32_e32 v25, v25, v40
	v_mul_f32_e32 v22, v22, v23
	v_mul_f32_e32 v19, v18, v19
	v_cvt_pk_bf16_f32 v17, v21, v22
	v_ashrrev_i32_e32 v33, 31, v32
	v_mul_f32_e32 v23, v30, v31
	v_mul_f32_e32 v24, v24, v25
	v_cvt_pk_bf16_f32 v18, v23, v28
	v_cvt_pk_bf16_f32 v19, v24, v19
	global_store_dwordx4 v[26:27], v[16:19], off
	v_mov_b32_e32 v34, v12
	v_mov_b32_e32 v35, v4
	v_mov_b32_e32 v4, v13
	v_mov_b32_e32 v12, v14
	v_mov_b32_e32 v13, v6
	v_mov_b32_e32 v6, v15
	v_mov_b32_e32 v14, v8
	v_mov_b32_e32 v15, v0
	v_mov_b32_e32 v0, v9
	v_mov_b32_e32 v8, v10
	v_mov_b32_e32 v9, v2
	v_mov_b32_e32 v2, v11
	s_waitcnt vmcnt(1)
	v_pk_add_f32 v[236:237], v[236:237], v[238:239]
	v_pk_add_f32 v[240:241], v[240:241], v[242:243]
	v_pk_add_f32 v[244:245], v[244:245], v[246:247]
	v_pk_add_f32 v[248:249], v[248:249], v[250:251]
	v_pk_add_f32 v[236:237], v[236:237], v[240:241]
	v_pk_add_f32 v[244:245], v[244:245], v[248:249]
	s_nop 0
	v_pk_add_f32 v[236:237], v[236:237], v[244:245]
	s_nop 0
	v_add_f32_e32 v10, v236, v237
	v_fmamk_f32 v10, v10, 0x3a800000, v152
	v_mul_f32_e32 v11, 0x4b800000, v10
	v_cmp_gt_f32_e32 vcc, s52, v10
	s_nop 1
	v_cndmask_b32_e32 v10, v10, v11, vcc
	v_rsq_f32_e32 v16, v10
	v_mad_i64_i32 v[10:11], s[26:27], v32, s53, v[120:121]
	v_lshl_add_u64 v[10:11], v[10:11], 0, v[122:123]
	v_mul_f32_e32 v17, 0x45800000, v16
	v_cndmask_b32_e32 v16, v16, v17, vcc
	v_pk_mul_f32 v[2:3], v[2:3], v[16:17] op_sel_hi:[1,0]
	v_pk_mul_f32 v[18:19], v[34:35], v[16:17] op_sel_hi:[1,0]
	v_pk_mul_f32 v[4:5], v[4:5], v[16:17] op_sel_hi:[1,0]
	v_pk_mul_f32 v[12:13], v[12:13], v[16:17] op_sel_hi:[1,0]
	v_pk_mul_f32 v[6:7], v[6:7], v[16:17] op_sel_hi:[1,0]
	v_pk_mul_f32 v[14:15], v[14:15], v[16:17] op_sel_hi:[1,0]
	v_pk_mul_f32 v[0:1], v[0:1], v[16:17] op_sel_hi:[1,0]
	v_pk_mul_f32 v[8:9], v[8:9], v[16:17] op_sel_hi:[1,0]
	v_mul_f32_e32 v25, 0xbfb8aa3b, v3
	v_mul_f32_e32 v16, 0xbfb8aa3b, v19
	v_mul_f32_e32 v17, 0xbfb8aa3b, v5
	v_mul_f32_e32 v20, 0xbfb8aa3b, v13
	v_mul_f32_e32 v21, 0xbfb8aa3b, v7
	v_mul_f32_e32 v22, 0xbfb8aa3b, v15
	v_mul_f32_e32 v23, 0xbfb8aa3b, v1
	v_mul_f32_e32 v24, 0xbfb8aa3b, v9
	v_exp_f32_e32 v25, v25
	v_exp_f32_e32 v16, v16
	v_exp_f32_e32 v17, v17
	v_exp_f32_e32 v20, v20
	v_exp_f32_e32 v21, v21
	v_exp_f32_e32 v22, v22
	v_exp_f32_e32 v23, v23
	v_exp_f32_e32 v24, v24
	v_add_f32_e32 v25, 1.0, v25
	v_add_f32_e32 v16, 1.0, v16
	v_add_f32_e32 v17, 1.0, v17
	v_add_f32_e32 v20, 1.0, v20
	v_add_f32_e32 v21, 1.0, v21
	v_add_f32_e32 v22, 1.0, v22
	v_add_f32_e32 v23, 1.0, v23
	v_add_f32_e32 v24, 1.0, v24
	v_rcp_f32_e32 v25, v25
	v_rcp_f32_e32 v16, v16
	v_rcp_f32_e32 v17, v17
	v_rcp_f32_e32 v20, v20
	v_rcp_f32_e32 v21, v21
	v_rcp_f32_e32 v22, v22
	v_rcp_f32_e32 v23, v23
	v_rcp_f32_e32 v24, v24
	v_mul_f32_e32 v3, v3, v25
	v_mul_f32_e32 v16, v19, v16
	v_mul_f32_e32 v5, v5, v17
	v_mul_f32_e32 v13, v13, v20
	v_mul_f32_e32 v7, v7, v21
	v_mul_f32_e32 v15, v15, v22
	v_mul_f32_e32 v1, v1, v23
	v_mul_f32_e32 v9, v9, v24
	v_mul_f32_e32 v3, v2, v3
	s_andn2_b64 vcc, exec, s[6:7]
	s_mov_b64 s[6:7], -1
	v_mul_f32_e32 v16, v18, v16
	v_mul_f32_e32 v4, v4, v5
	v_mul_f32_e32 v5, v12, v13
	v_mul_f32_e32 v6, v6, v7
	v_mul_f32_e32 v7, v14, v15
	v_mul_f32_e32 v12, v0, v1
	v_mul_f32_e32 v8, v8, v9
	v_cvt_pk_bf16_f32 v0, v16, v4
	v_cvt_pk_bf16_f32 v1, v5, v6
	v_cvt_pk_bf16_f32 v2, v7, v12
	v_cvt_pk_bf16_f32 v3, v8, v3
	global_store_dwordx4 v[10:11], v[0:3], off
	s_cbranch_vccnz .LBB0_3315
	s_andn2_b64 vcc, exec, s[0:1]
	s_cbranch_vccnz .LBB0_3314
	s_barrier
	s_branch .LBB0_3314
